# norm-phase ctx slab sums with hoisted loads; split-K partial epilogue gate vectors loaded once
# speedup vs baseline: 1.0517x; 1.0118x over previous
; __device__ __forceinline__ void norm_phase(float* __restrict__ X, bf16_t* __restrict__ H, const float* __restrict__ nw, const float* __restrict__ modL, const float* __restrict__ modC, int sh_off, int sc_off, ...
;     ...
;     if (r < NCTX && nsl > 0) {
;       for (int sl = 0; sl < nsl; ++sl) { const float* pr = part + ((size_t)sl * NCTX + r) * DM;
; #pragma unroll
;         for (int i = 0; i < 4; ++i) v[i] += *(const f32x4*)(pr + i * 256 + lane * 4); }
; #pragma unroll
;       for (int i = 0; i < 4; ++i) *(f32x4*)(xr + i * 256 + lane * 4) = v[i];
;     }
.LBB0_546:
	s_or_b64 exec, exec, s[26:27]
	s_and_b64 s[6:7], exec, s[6:7]
	s_or_b64 s[18:19], s[6:7], s[18:19]
	v_cmp_gt_i32_e64 s[6:7], s73, v56
	s_and_b64 s[24:25], s[4:5], s[6:7]
	s_and_saveexec_b64 s[26:27], s[24:25]
	s_cbranch_execz .LBB0_535
	v_lshl_add_u64 v[56:57], v[42:43], 0, v[40:41]
	v_add_co_u32_e32 v62, vcc, 0x9bce000, v56
	s_nop 1
	v_addc_co_u32_e32 v63, vcc, 0, v57, vcc
	global_load_dwordx4 v[74:77], v[62:63], off offset:256
	global_load_dwordx4 v[78:81], v[62:63], off offset:1280
	global_load_dwordx4 v[82:85], v[62:63], off offset:2304
	global_load_dwordx4 v[86:89], v[62:63], off offset:3328
	v_add_co_u32_e32 v62, vcc, 0x9cce000, v56
	s_nop 1
	v_addc_co_u32_e32 v63, vcc, 0, v57, vcc
	global_load_dwordx4 v[90:93], v[62:63], off offset:256
	global_load_dwordx4 v[94:97], v[62:63], off offset:1280
	global_load_dwordx4 v[98:101], v[62:63], off offset:2304
	global_load_dwordx4 v[102:105], v[62:63], off offset:3328
	v_add_co_u32_e32 v62, vcc, 0x9dce000, v56
	s_nop 1
	v_addc_co_u32_e32 v63, vcc, 0, v57, vcc
	global_load_dwordx4 v[106:109], v[62:63], off offset:256
	global_load_dwordx4 v[110:113], v[62:63], off offset:1280
	global_load_dwordx4 v[114:117], v[62:63], off offset:2304
	global_load_dwordx4 v[118:121], v[62:63], off offset:3328
	v_add_co_u32_e32 v62, vcc, 0x9ece000, v56
	s_nop 1
	v_addc_co_u32_e32 v63, vcc, 0, v57, vcc
	global_load_dwordx4 v[122:125], v[62:63], off offset:256
	global_load_dwordx4 v[126:129], v[62:63], off offset:1280
	global_load_dwordx4 v[130:133], v[62:63], off offset:2304
	global_load_dwordx4 v[134:137], v[62:63], off offset:3328
	s_waitcnt vmcnt(15)
	v_pk_add_f32 v[30:31], v[30:31], v[76:77]
	v_pk_add_f32 v[28:29], v[28:29], v[74:75]
	s_waitcnt vmcnt(14)
	v_pk_add_f32 v[26:27], v[26:27], v[80:81]
	v_pk_add_f32 v[24:25], v[24:25], v[78:79]
	s_waitcnt vmcnt(13)
	v_pk_add_f32 v[22:23], v[22:23], v[84:85]
	v_pk_add_f32 v[20:21], v[20:21], v[82:83]
	s_waitcnt vmcnt(12)
	v_pk_add_f32 v[34:35], v[34:35], v[88:89]
	v_pk_add_f32 v[32:33], v[32:33], v[86:87]
	s_waitcnt vmcnt(11)
	v_pk_add_f32 v[30:31], v[30:31], v[92:93]
	v_pk_add_f32 v[28:29], v[28:29], v[90:91]
	s_waitcnt vmcnt(10)
	v_pk_add_f32 v[26:27], v[26:27], v[96:97]
	v_pk_add_f32 v[24:25], v[24:25], v[94:95]
	s_waitcnt vmcnt(9)
	v_pk_add_f32 v[22:23], v[22:23], v[100:101]
	v_pk_add_f32 v[20:21], v[20:21], v[98:99]
	s_waitcnt vmcnt(8)
	v_pk_add_f32 v[34:35], v[34:35], v[104:105]
	v_pk_add_f32 v[32:33], v[32:33], v[102:103]
	s_waitcnt vmcnt(7)
	v_pk_add_f32 v[30:31], v[30:31], v[108:109]
	v_pk_add_f32 v[28:29], v[28:29], v[106:107]
	s_waitcnt vmcnt(6)
	v_pk_add_f32 v[26:27], v[26:27], v[112:113]
	v_pk_add_f32 v[24:25], v[24:25], v[110:111]
	s_waitcnt vmcnt(5)
	v_pk_add_f32 v[22:23], v[22:23], v[116:117]
	v_pk_add_f32 v[20:21], v[20:21], v[114:115]
	s_waitcnt vmcnt(4)
	v_pk_add_f32 v[34:35], v[34:35], v[120:121]
	v_pk_add_f32 v[32:33], v[32:33], v[118:119]
	s_waitcnt vmcnt(3)
	v_pk_add_f32 v[30:31], v[30:31], v[124:125]
	v_pk_add_f32 v[28:29], v[28:29], v[122:123]
	s_waitcnt vmcnt(2)
	v_pk_add_f32 v[26:27], v[26:27], v[128:129]
	v_pk_add_f32 v[24:25], v[24:25], v[126:127]
	s_waitcnt vmcnt(1)
	v_pk_add_f32 v[22:23], v[22:23], v[132:133]
	v_pk_add_f32 v[20:21], v[20:21], v[130:131]
	s_waitcnt vmcnt(0)
	v_pk_add_f32 v[34:35], v[34:35], v[136:137]
	v_pk_add_f32 v[32:33], v[32:33], v[134:135]
	v_add_co_u32_e32 v62, vcc, 0x9fce000, v56
	s_nop 1
	v_addc_co_u32_e32 v63, vcc, 0, v57, vcc
	global_load_dwordx4 v[74:77], v[62:63], off offset:256
	global_load_dwordx4 v[78:81], v[62:63], off offset:1280
	global_load_dwordx4 v[82:85], v[62:63], off offset:2304
	global_load_dwordx4 v[86:89], v[62:63], off offset:3328
	v_add_co_u32_e32 v62, vcc, 0xa0ce000, v56
	s_nop 1
	v_addc_co_u32_e32 v63, vcc, 0, v57, vcc
	global_load_dwordx4 v[90:93], v[62:63], off offset:256
	global_load_dwordx4 v[94:97], v[62:63], off offset:1280
	global_load_dwordx4 v[98:101], v[62:63], off offset:2304
	global_load_dwordx4 v[102:105], v[62:63], off offset:3328
	v_add_co_u32_e32 v62, vcc, 0xa1ce000, v56
	s_nop 1
	v_addc_co_u32_e32 v63, vcc, 0, v57, vcc
	global_load_dwordx4 v[106:109], v[62:63], off offset:256
	global_load_dwordx4 v[110:113], v[62:63], off offset:1280
	global_load_dwordx4 v[114:117], v[62:63], off offset:2304
	global_load_dwordx4 v[118:121], v[62:63], off offset:3328
	v_add_co_u32_e32 v62, vcc, 0xa2ce000, v56
	s_nop 1
	v_addc_co_u32_e32 v63, vcc, 0, v57, vcc
	global_load_dwordx4 v[122:125], v[62:63], off offset:256
	global_load_dwordx4 v[126:129], v[62:63], off offset:1280
	global_load_dwordx4 v[130:133], v[62:63], off offset:2304
	global_load_dwordx4 v[134:137], v[62:63], off offset:3328
	s_waitcnt vmcnt(15)
	v_pk_add_f32 v[30:31], v[30:31], v[76:77]
	v_pk_add_f32 v[28:29], v[28:29], v[74:75]
	s_waitcnt vmcnt(14)
	v_pk_add_f32 v[26:27], v[26:27], v[80:81]
	v_pk_add_f32 v[24:25], v[24:25], v[78:79]
	s_waitcnt vmcnt(13)
	v_pk_add_f32 v[22:23], v[22:23], v[84:85]
	v_pk_add_f32 v[20:21], v[20:21], v[82:83]
	s_waitcnt vmcnt(12)
	v_pk_add_f32 v[34:35], v[34:35], v[88:89]
	v_pk_add_f32 v[32:33], v[32:33], v[86:87]
	s_waitcnt vmcnt(11)
	v_pk_add_f32 v[30:31], v[30:31], v[92:93]
	v_pk_add_f32 v[28:29], v[28:29], v[90:91]
	s_waitcnt vmcnt(10)
	v_pk_add_f32 v[26:27], v[26:27], v[96:97]
	v_pk_add_f32 v[24:25], v[24:25], v[94:95]
	s_waitcnt vmcnt(9)
	v_pk_add_f32 v[22:23], v[22:23], v[100:101]
	v_pk_add_f32 v[20:21], v[20:21], v[98:99]
	s_waitcnt vmcnt(8)
	v_pk_add_f32 v[34:35], v[34:35], v[104:105]
	v_pk_add_f32 v[32:33], v[32:33], v[102:103]
	s_waitcnt vmcnt(7)
	v_pk_add_f32 v[30:31], v[30:31], v[108:109]
	v_pk_add_f32 v[28:29], v[28:29], v[106:107]
	s_waitcnt vmcnt(6)
	v_pk_add_f32 v[26:27], v[26:27], v[112:113]
	v_pk_add_f32 v[24:25], v[24:25], v[110:111]
	s_waitcnt vmcnt(5)
	v_pk_add_f32 v[22:23], v[22:23], v[116:117]
	v_pk_add_f32 v[20:21], v[20:21], v[114:115]
	s_waitcnt vmcnt(4)
	v_pk_add_f32 v[34:35], v[34:35], v[120:121]
	v_pk_add_f32 v[32:33], v[32:33], v[118:119]
	s_waitcnt vmcnt(3)
	v_pk_add_f32 v[30:31], v[30:31], v[124:125]
	v_pk_add_f32 v[28:29], v[28:29], v[122:123]
	s_waitcnt vmcnt(2)
	v_pk_add_f32 v[26:27], v[26:27], v[128:129]
	v_pk_add_f32 v[24:25], v[24:25], v[126:127]
	s_waitcnt vmcnt(1)
	v_pk_add_f32 v[22:23], v[22:23], v[132:133]
	v_pk_add_f32 v[20:21], v[20:21], v[130:131]
	s_waitcnt vmcnt(0)
	v_pk_add_f32 v[34:35], v[34:35], v[136:137]
	v_pk_add_f32 v[32:33], v[32:33], v[134:135]
	v_lshl_add_u64 v[56:57], v[46:47], 0, v[40:41]
	global_store_dwordx4 v[56:57], v[28:31], off
	global_store_dwordx4 v[56:57], v[24:27], off offset:1024
	global_store_dwordx4 v[56:57], v[20:23], off offset:2048
	global_store_dwordx4 v[56:57], v[32:35], off offset:3072
	s_branch .LBB0_535

; #define PG8_STAGE(bufoff, gbase, voff) do { _Pragma("unroll") for (int _i = 0; _i < 2; ++_i) \
;     __builtin_amdgcn_global_load_lds((const unsigned*)((const char*)(gbase) + (voff)[_i]), (LAS unsigned*)(lds + (bufoff) + ldsw + _i * 8192), 16, 0, 0); } while (0)
; #define PG8_LDA(dst, b, h) do { _Pragma("unroll") for (int m = 0; m < 4; ++m) _Pragma("unroll") for (int k = 0; k < 2; ++k) dst[m][k] = *(const LAS bf16x8*)(lds + PG8_SA(b, h) + aoff + m * 2048 + k * 1024); } while (0)
; #define PG8_LDB(dst, b, h) do { _Pragma("unroll") for (int n = 0; n < 2; ++n) _Pragma("unroll") for (int k = 0; k < 2; ++k) dst[n][k] = *(const LAS bf16x8*)(lds + PG8_SB(b, h) + boff + n * 2048 + k * 1024); } while (0)
; #define PG8_MMA(ai, bj, At, Bt) do { __builtin_amdgcn_s_setprio(1); _Pragma("unroll") for (int m = 0; m < 4; ++m) _Pragma("unroll") for (int n = 0; n < 2; ++n) _Pragma("unroll") for (int k = 0; k < 2; ++k) \
;     acc[ai][bj][m][n] = __builtin_amdgcn_mfma_f32_16x16x32_bf16(Bt[n][k], At[m][k], acc[ai][bj][m][n], 0, 0, 0); __builtin_amdgcn_s_setprio(0); } while (0)
; #define PG8_WAIT_V(n) asm volatile("s_waitcnt vmcnt(" #n ")" ::: "memory")
; #define PG8_WAIT_L(n) asm volatile("s_waitcnt lgkmcnt(" #n ")" ::: "memory")
; #define PG8_BAR __builtin_amdgcn_s_barrier()
; #define PG8_SCHED __builtin_amdgcn_sched_barrier(0)
; template <class Epi, class Sched>
; __device__ __forceinline__ void gemm_phase(LAS unsigned char* lds, const Gemm g, const Sched& S, const Epi& E) {
;     ...
;     for (int t = 0; t < nt; t += 2) {
;       const bool last = (t == nt - 2);
;       const char* a1 = cA + (size_t)(t + 1) * kstep;
;       const char* a2 = last ? nA : cA + (size_t)(t + 2) * kstep; const char* b2 = last ? nB : cB + (size_t)(t + 2) * kstep;
;       const char* a3 = a2 + kstep; const char* b3 = b2 + kstep;
;       PG8_LDB(B0, 0, 0); PG8_SCHED; PG8_LDA(At, 0, 0); PG8_STAGE(PG8_SA(1, 1), a1 + hstepA, voffA);
;       PG8_WAIT_L(8); PG8_BAR; PG8_WAIT_L(0); PG8_MMA(0, 0, At, B0); PG8_BAR; PG8_SCHED;
;       PG8_LDB(B1, 0, 1); PG8_STAGE(PG8_SB(0, 0), b2, voffB);
;       PG8_BAR; PG8_WAIT_L(0); PG8_MMA(0, 1, At, B1); PG8_BAR;
;       PG8_LDA(At, 0, 1); PG8_STAGE(PG8_SA(0, 0), a2, voffA);
;       PG8_BAR; PG8_WAIT_L(0); PG8_MMA(1, 0, At, B0); PG8_BAR; PG8_SCHED;
;       PG8_STAGE(PG8_SB(0, 1), b2 + hstepB, voffB);
;       PG8_WAIT_V(6); PG8_BAR; PG8_MMA(1, 1, At, B1); PG8_BAR;
.LBB0_2615:
	s_add_u32 s29, s20, s28
	s_addc_u32 s49, s21, 0
	s_add_u32 s38, s29, 0x100
	s_addc_u32 s39, s49, 0
	s_and_b64 s[36:37], s[26:27], exec
	s_cselect_b32 s39, s11, s39
	s_cselect_b32 s38, s83, s38
	s_add_u32 s28, s18, s28
	s_addc_u32 s36, s19, 0
	s_add_u32 s28, s28, 0x100
	s_addc_u32 s36, s36, 0
	s_add_i32 s76, 16, 0x10000
	s_and_b64 s[26:27], s[26:27], exec
	s_cselect_b32 s47, s9, s36
	s_cselect_b32 s46, s84, s28
	s_add_u32 s48, s29, 0x40080
	s_addc_u32 s49, s49, 0
	s_add_i32 vcc_hi, s76, s51
	s_add_i32 m0, s58, 0xc000
	s_add_i32 s77, s58, 0xe000
	s_add_i32 vcc_lo, 16, 0x14000
	s_add_i32 s95, vcc_hi, 0x2000
	s_add_u32 s36, s46, 0x40000
	v_add_u32_e32 v154, s76, v145
	s_addc_u32 s37, s47, 0
	s_add_i32 s90, vcc_lo, s51
	ds_read_b128 v[150:153], v154
	ds_read_b128 v[158:161], v154 offset:1024
	ds_read_b128 v[162:165], v154 offset:2048
	ds_read_b128 v[166:169], v154 offset:3072
	s_add_i32 s89, s90, 0x2000
	s_add_i32 s88, 16, 0x18000
	s_add_u32 s28, s38, 0x40000
	s_addc_u32 s29, s39, 0
	s_add_i32 s87, s88, s51
	s_add_i32 s86, 16, 0x1c000
	s_add_i32 s85, s87, 0x2000
	s_add_u32 s26, s46, 0x40080
	s_addc_u32 s27, s47, 0
	s_add_i32 s94, s86, s51
	s_add_i32 s91, s94, 0x2000
	v_lshl_add_u64 v[154:155], s[48:49], 0, v[130:131]
	ds_read_b128 v[170:173], v157
	ds_read_b128 v[174:177], v157 offset:1024
	ds_read_b128 v[178:181], v157 offset:2048
	ds_read_b128 v[182:185], v157 offset:3072
	ds_read_b128 v[198:201], v157 offset:4096
	ds_read_b128 v[214:217], v157 offset:5120
	ds_read_b128 v[218:221], v157 offset:6144
	ds_read_b128 v[222:225], v157 offset:7168
	global_load_lds_dwordx4 v[154:155], off
	v_lshl_add_u64 v[154:155], s[48:49], 0, v[128:129]
	s_mov_b32 m0, s77
	s_nop 0
	global_load_lds_dwordx4 v[154:155], off
	s_waitcnt lgkmcnt(8)
	s_barrier
	s_waitcnt lgkmcnt(0)
	s_setprio 1
	s_waitcnt lgkmcnt(0)
	v_mfma_f32_16x16x32_bf16 v[124:127], v[150:153], v[170:173], v[124:127]
	v_mfma_f32_16x16x32_bf16 v[120:123], v[162:165], v[170:173], v[120:123]
	v_mfma_f32_16x16x32_bf16 v[112:115], v[150:153], v[178:181], v[112:115]
	v_mfma_f32_16x16x32_bf16 v[104:107], v[162:165], v[178:181], v[104:107]
	v_mfma_f32_16x16x32_bf16 v[96:99], v[150:153], v[198:201], v[96:99]
	v_mfma_f32_16x16x32_bf16 v[88:91], v[162:165], v[198:201], v[88:91]
	v_mfma_f32_16x16x32_bf16 v[80:83], v[150:153], v[218:221], v[80:83]
	v_mfma_f32_16x16x32_bf16 v[72:75], v[162:165], v[218:221], v[72:75]
	v_mfma_f32_16x16x32_bf16 v[124:127], v[158:161], v[174:177], v[124:127]
	v_mfma_f32_16x16x32_bf16 v[120:123], v[166:169], v[174:177], v[120:123]
	v_mfma_f32_16x16x32_bf16 v[112:115], v[158:161], v[182:185], v[112:115]
	v_mfma_f32_16x16x32_bf16 v[104:107], v[166:169], v[182:185], v[104:107]
	v_mfma_f32_16x16x32_bf16 v[96:99], v[158:161], v[214:217], v[96:99]
	v_mfma_f32_16x16x32_bf16 v[88:91], v[166:169], v[214:217], v[88:91]
	v_mfma_f32_16x16x32_bf16 v[80:83], v[158:161], v[222:225], v[80:83]
	v_mfma_f32_16x16x32_bf16 v[72:75], v[166:169], v[222:225], v[72:75]
	s_setprio 0
	s_barrier
	v_add_u32_e32 v154, vcc_lo, v145
	s_mov_b32 m0, vcc_hi
	ds_read_b128 v[226:229], v154
	ds_read_b128 v[230:233], v154 offset:1024
	ds_read_b128 v[234:237], v154 offset:2048
	ds_read_b128 v[238:241], v154 offset:3072
	v_lshl_add_u64 v[154:155], s[46:47], 0, v[130:131]
	global_load_lds_dwordx4 v[154:155], off
	v_lshl_add_u64 v[242:243], s[46:47], 0, v[128:129]
	s_mov_b32 m0, s95
	s_nop 0
	global_load_lds_dwordx4 v[242:243], off
	s_barrier
	s_waitcnt lgkmcnt(0)
	s_setprio 1
	s_waitcnt lgkmcnt(0)
	v_mfma_f32_16x16x32_bf16 v[116:119], v[226:229], v[170:173], v[116:119]
	v_mfma_f32_16x16x32_bf16 v[108:111], v[234:237], v[170:173], v[108:111]
	v_mfma_f32_16x16x32_bf16 v[100:103], v[226:229], v[178:181], v[100:103]
	v_mfma_f32_16x16x32_bf16 v[92:95], v[234:237], v[178:181], v[92:95]
	v_mfma_f32_16x16x32_bf16 v[84:87], v[226:229], v[198:201], v[84:87]
	v_mfma_f32_16x16x32_bf16 v[76:79], v[234:237], v[198:201], v[76:79]
	v_mfma_f32_16x16x32_bf16 v[68:71], v[226:229], v[218:221], v[68:71]
	v_mfma_f32_16x16x32_bf16 v[64:67], v[234:237], v[218:221], v[64:67]
	v_mfma_f32_16x16x32_bf16 v[116:119], v[230:233], v[174:177], v[116:119]
	v_mfma_f32_16x16x32_bf16 v[108:111], v[238:241], v[174:177], v[108:111]
	v_mfma_f32_16x16x32_bf16 v[100:103], v[230:233], v[182:185], v[100:103]
	v_mfma_f32_16x16x32_bf16 v[92:95], v[238:241], v[182:185], v[92:95]
	v_mfma_f32_16x16x32_bf16 v[84:87], v[230:233], v[214:217], v[84:87]
	v_mfma_f32_16x16x32_bf16 v[76:79], v[238:241], v[214:217], v[76:79]
	v_mfma_f32_16x16x32_bf16 v[68:71], v[230:233], v[222:225], v[68:71]
	v_mfma_f32_16x16x32_bf16 v[64:67], v[238:241], v[222:225], v[64:67]
	s_setprio 0
	s_mov_b32 m0, s58
	v_lshl_add_u64 v[244:245], s[38:39], 0, v[130:131]
	s_barrier
	ds_read_b128 v[170:173], v157 offset:16384
	ds_read_b128 v[174:177], v157 offset:17408
	ds_read_b128 v[178:181], v157 offset:18432
	ds_read_b128 v[182:185], v157 offset:19456
	ds_read_b128 v[198:201], v157 offset:20480
	ds_read_b128 v[214:217], v157 offset:21504
	ds_read_b128 v[218:221], v157 offset:22528
	ds_read_b128 v[222:225], v157 offset:23552
	global_load_lds_dwordx4 v[244:245], off
	v_lshl_add_u64 v[246:247], s[38:39], 0, v[128:129]
	s_mov_b32 m0, s59
	s_nop 0
	global_load_lds_dwordx4 v[246:247], off
	s_barrier
; #define PG8_STAGE(bufoff, gbase, voff) do { _Pragma("unroll") for (int _i = 0; _i < 2; ++_i) \
;     __builtin_amdgcn_global_load_lds((const unsigned*)((const char*)(gbase) + (voff)[_i]), (LAS unsigned*)(lds + (bufoff) + ldsw + _i * 8192), 16, 0, 0); } while (0)
; #define PG8_LDA(dst, b, h) do { _Pragma("unroll") for (int m = 0; m < 4; ++m) _Pragma("unroll") for (int k = 0; k < 2; ++k) dst[m][k] = *(const LAS bf16x8*)(lds + PG8_SA(b, h) + aoff + m * 2048 + k * 1024); } while (0)
; #define PG8_LDB(dst, b, h) do { _Pragma("unroll") for (int n = 0; n < 2; ++n) _Pragma("unroll") for (int k = 0; k < 2; ++k) dst[n][k] = *(const LAS bf16x8*)(lds + PG8_SB(b, h) + boff + n * 2048 + k * 1024); } while (0)
; #define PG8_MMA(ai, bj, At, Bt) do { __builtin_amdgcn_s_setprio(1); _Pragma("unroll") for (int m = 0; m < 4; ++m) _Pragma("unroll") for (int n = 0; n < 2; ++n) _Pragma("unroll") for (int k = 0; k < 2; ++k) \
;     acc[ai][bj][m][n] = __builtin_amdgcn_mfma_f32_16x16x32_bf16(Bt[n][k], At[m][k], acc[ai][bj][m][n], 0, 0, 0); __builtin_amdgcn_s_setprio(0); } while (0)
; #define PG8_WAIT_V(n) asm volatile("s_waitcnt vmcnt(" #n ")" ::: "memory")
; #define PG8_WAIT_L(n) asm volatile("s_waitcnt lgkmcnt(" #n ")" ::: "memory")
; #define PG8_BAR __builtin_amdgcn_s_barrier()
; #define PG8_SCHED __builtin_amdgcn_sched_barrier(0)
; template <class Epi, class Sched>
; __device__ __forceinline__ void gemm_phase(LAS unsigned char* lds, const Gemm g, const Sched& S, const Epi& E) {
;     ...
;       PG8_BAR; PG8_WAIT_L(0); PG8_MMA(1, 0, At, B0); PG8_BAR; PG8_SCHED;
;       PG8_STAGE(PG8_SB(0, 1), b2 + hstepB, voffB);
;       PG8_WAIT_V(6); PG8_BAR; PG8_MMA(1, 1, At, B1); PG8_BAR;
;       PG8_LDB(B0, 1, 0); PG8_SCHED; PG8_LDA(At, 1, 0); PG8_STAGE(PG8_SA(0, 1), a2 + hstepA, voffA);
;       PG8_WAIT_L(8); PG8_BAR; PG8_WAIT_L(0); PG8_MMA(0, 0, At, B0); PG8_BAR; PG8_SCHED;
;       PG8_LDB(B1, 1, 1); PG8_STAGE(PG8_SB(1, 0), b3, voffB);
;       PG8_BAR; PG8_WAIT_L(0); PG8_MMA(0, 1, At, B1); PG8_BAR;
	s_waitcnt lgkmcnt(0)
	s_setprio 1
	s_waitcnt lgkmcnt(0)
	v_mfma_f32_16x16x32_bf16 v[60:63], v[150:153], v[170:173], v[60:63]
	v_mfma_f32_16x16x32_bf16 v[56:59], v[162:165], v[170:173], v[56:59]
	v_mfma_f32_16x16x32_bf16 v[48:51], v[150:153], v[178:181], v[48:51]
	v_mfma_f32_16x16x32_bf16 v[40:43], v[162:165], v[178:181], v[40:43]
	v_mfma_f32_16x16x32_bf16 v[32:35], v[150:153], v[198:201], v[32:35]
	v_mfma_f32_16x16x32_bf16 v[24:27], v[162:165], v[198:201], v[24:27]
	v_mfma_f32_16x16x32_bf16 v[16:19], v[150:153], v[218:221], v[16:19]
	v_mfma_f32_16x16x32_bf16 v[8:11], v[162:165], v[218:221], v[8:11]
	v_mfma_f32_16x16x32_bf16 v[60:63], v[158:161], v[174:177], v[60:63]
	v_mfma_f32_16x16x32_bf16 v[56:59], v[166:169], v[174:177], v[56:59]
	v_mfma_f32_16x16x32_bf16 v[48:51], v[158:161], v[182:185], v[48:51]
	v_mfma_f32_16x16x32_bf16 v[40:43], v[166:169], v[182:185], v[40:43]
	v_mfma_f32_16x16x32_bf16 v[32:35], v[158:161], v[214:217], v[32:35]
	v_mfma_f32_16x16x32_bf16 v[24:27], v[166:169], v[214:217], v[24:27]
	v_mfma_f32_16x16x32_bf16 v[16:19], v[158:161], v[222:225], v[16:19]
	v_mfma_f32_16x16x32_bf16 v[8:11], v[166:169], v[222:225], v[8:11]
	s_setprio 0
	s_barrier
	s_mov_b32 m0, s90
	v_lshl_add_u64 v[150:151], s[36:37], 0, v[130:131]
	global_load_lds_dwordx4 v[150:151], off
	v_lshl_add_u64 v[150:151], s[36:37], 0, v[128:129]
	s_mov_b32 m0, s89
	s_nop 0
	global_load_lds_dwordx4 v[150:151], off
	s_waitcnt vmcnt(6)
	s_barrier
	s_setprio 1
	v_mfma_f32_16x16x32_bf16 v[52:55], v[226:229], v[170:173], v[52:55]
	v_mfma_f32_16x16x32_bf16 v[44:47], v[234:237], v[170:173], v[44:47]
	v_mfma_f32_16x16x32_bf16 v[36:39], v[226:229], v[178:181], v[36:39]
	v_mfma_f32_16x16x32_bf16 v[28:31], v[234:237], v[178:181], v[28:31]
	v_mfma_f32_16x16x32_bf16 v[20:23], v[226:229], v[198:201], v[20:23]
	v_mfma_f32_16x16x32_bf16 v[12:15], v[234:237], v[198:201], v[12:15]
	v_mfma_f32_16x16x32_bf16 v[4:7], v[226:229], v[218:221], v[4:7]
	v_mfma_f32_16x16x32_bf16 v[0:3], v[234:237], v[218:221], v[0:3]
	v_mfma_f32_16x16x32_bf16 v[52:55], v[230:233], v[174:177], v[52:55]
	v_mfma_f32_16x16x32_bf16 v[44:47], v[238:241], v[174:177], v[44:47]
	v_mfma_f32_16x16x32_bf16 v[36:39], v[230:233], v[182:185], v[36:39]
	v_mfma_f32_16x16x32_bf16 v[28:31], v[238:241], v[182:185], v[28:31]
	v_mfma_f32_16x16x32_bf16 v[20:23], v[230:233], v[214:217], v[20:23]
	v_mfma_f32_16x16x32_bf16 v[12:15], v[238:241], v[214:217], v[12:15]
	v_mfma_f32_16x16x32_bf16 v[4:7], v[230:233], v[222:225], v[4:7]
	v_mfma_f32_16x16x32_bf16 v[0:3], v[238:241], v[222:225], v[0:3]
	s_setprio 0
	v_add_u32_e32 v166, s88, v145
	s_barrier
	ds_read_b128 v[150:153], v166
	ds_read_b128 v[158:161], v166 offset:1024
	ds_read_b128 v[162:165], v166 offset:2048
	ds_read_b128 v[166:169], v166 offset:3072
	s_mov_b32 m0, s66
	v_lshl_add_u64 v[226:227], s[28:29], 0, v[130:131]
	ds_read_b128 v[170:173], v157 offset:32768
	ds_read_b128 v[174:177], v157 offset:33792
	ds_read_b128 v[178:181], v157 offset:34816
	ds_read_b128 v[182:185], v157 offset:35840
	ds_read_b128 v[198:201], v157 offset:36864
	ds_read_b128 v[214:217], v157 offset:37888
	ds_read_b128 v[218:221], v157 offset:38912
	ds_read_b128 v[222:225], v157 offset:39936
	global_load_lds_dwordx4 v[226:227], off
	v_lshl_add_u64 v[226:227], s[28:29], 0, v[128:129]
	s_mov_b32 m0, s67
	s_nop 0
	global_load_lds_dwordx4 v[226:227], off
	s_waitcnt lgkmcnt(8)
	s_barrier
	s_waitcnt lgkmcnt(0)
	s_setprio 1
	s_waitcnt lgkmcnt(0)
	v_mfma_f32_16x16x32_bf16 v[124:127], v[150:153], v[170:173], v[124:127]
	v_mfma_f32_16x16x32_bf16 v[120:123], v[162:165], v[170:173], v[120:123]
	v_mfma_f32_16x16x32_bf16 v[112:115], v[150:153], v[178:181], v[112:115]
	v_mfma_f32_16x16x32_bf16 v[104:107], v[162:165], v[178:181], v[104:107]
	v_mfma_f32_16x16x32_bf16 v[96:99], v[150:153], v[198:201], v[96:99]
	v_mfma_f32_16x16x32_bf16 v[88:91], v[162:165], v[198:201], v[88:91]
	v_mfma_f32_16x16x32_bf16 v[80:83], v[150:153], v[218:221], v[80:83]
	v_mfma_f32_16x16x32_bf16 v[72:75], v[162:165], v[218:221], v[72:75]
	v_mfma_f32_16x16x32_bf16 v[124:127], v[158:161], v[174:177], v[124:127]
	v_mfma_f32_16x16x32_bf16 v[120:123], v[166:169], v[174:177], v[120:123]
	v_mfma_f32_16x16x32_bf16 v[112:115], v[158:161], v[182:185], v[112:115]
	v_mfma_f32_16x16x32_bf16 v[104:107], v[166:169], v[182:185], v[104:107]
	v_mfma_f32_16x16x32_bf16 v[96:99], v[158:161], v[214:217], v[96:99]
	v_mfma_f32_16x16x32_bf16 v[88:91], v[166:169], v[214:217], v[88:91]
	v_mfma_f32_16x16x32_bf16 v[80:83], v[158:161], v[222:225], v[80:83]
	v_mfma_f32_16x16x32_bf16 v[72:75], v[166:169], v[222:225], v[72:75]
	s_setprio 0
	s_barrier
	s_mov_b32 m0, s87
	v_add_u32_e32 v189, s86, v145
	v_lshl_add_u64 v[154:155], v[154:155], 0, s[62:63]
	ds_read_b128 v[226:229], v189
	ds_read_b128 v[230:233], v189 offset:1024
	ds_read_b128 v[234:237], v189 offset:2048
	ds_read_b128 v[238:241], v189 offset:3072
	global_load_lds_dwordx4 v[154:155], off
	v_lshl_add_u64 v[154:155], v[242:243], 0, s[62:63]
	s_mov_b32 m0, s85
	s_nop 0
	global_load_lds_dwordx4 v[154:155], off
	s_barrier
; #define PG8_STAGE(bufoff, gbase, voff) do { _Pragma("unroll") for (int _i = 0; _i < 2; ++_i) \
;     __builtin_amdgcn_global_load_lds((const unsigned*)((const char*)(gbase) + (voff)[_i]), (LAS unsigned*)(lds + (bufoff) + ldsw + _i * 8192), 16, 0, 0); } while (0)
; #define PG8_LDA(dst, b, h) do { _Pragma("unroll") for (int m = 0; m < 4; ++m) _Pragma("unroll") for (int k = 0; k < 2; ++k) dst[m][k] = *(const LAS bf16x8*)(lds + PG8_SA(b, h) + aoff + m * 2048 + k * 1024); } while (0)
; #define PG8_MMA(ai, bj, At, Bt) do { __builtin_amdgcn_s_setprio(1); _Pragma("unroll") for (int m = 0; m < 4; ++m) _Pragma("unroll") for (int n = 0; n < 2; ++n) _Pragma("unroll") for (int k = 0; k < 2; ++k) \
;     acc[ai][bj][m][n] = __builtin_amdgcn_mfma_f32_16x16x32_bf16(Bt[n][k], At[m][k], acc[ai][bj][m][n], 0, 0, 0); __builtin_amdgcn_s_setprio(0); } while (0)
; #define PG8_WAIT_V(n) asm volatile("s_waitcnt vmcnt(" #n ")" ::: "memory")
; #define PG8_WAIT_L(n) asm volatile("s_waitcnt lgkmcnt(" #n ")" ::: "memory")
; #define PG8_BAR __builtin_amdgcn_s_barrier()
; #define PG8_SCHED __builtin_amdgcn_sched_barrier(0)
; template <class Epi, class Sched>
; __device__ __forceinline__ void gemm_phase(LAS unsigned char* lds, const Gemm g, const Sched& S, const Epi& E) {
;     ...
;       PG8_BAR; PG8_WAIT_L(0); PG8_MMA(0, 1, At, B1); PG8_BAR;
;       PG8_LDA(At, 1, 1); PG8_STAGE(PG8_SA(1, 0), a3, voffA);
;       PG8_BAR; PG8_WAIT_L(0); PG8_MMA(1, 0, At, B0); PG8_BAR; PG8_SCHED;
;       PG8_STAGE(PG8_SB(1, 1), b3 + hstepB, voffB);
;       PG8_WAIT_V(6); PG8_BAR; PG8_MMA(1, 1, At, B1); PG8_BAR;
	s_waitcnt lgkmcnt(0)
	s_setprio 1
	s_waitcnt lgkmcnt(0)
	v_mfma_f32_16x16x32_bf16 v[116:119], v[226:229], v[170:173], v[116:119]
	v_mfma_f32_16x16x32_bf16 v[108:111], v[234:237], v[170:173], v[108:111]
	v_mfma_f32_16x16x32_bf16 v[100:103], v[226:229], v[178:181], v[100:103]
	v_mfma_f32_16x16x32_bf16 v[92:95], v[234:237], v[178:181], v[92:95]
	v_mfma_f32_16x16x32_bf16 v[84:87], v[226:229], v[198:201], v[84:87]
	v_mfma_f32_16x16x32_bf16 v[76:79], v[234:237], v[198:201], v[76:79]
	v_mfma_f32_16x16x32_bf16 v[68:71], v[226:229], v[218:221], v[68:71]
	v_mfma_f32_16x16x32_bf16 v[64:67], v[234:237], v[218:221], v[64:67]
	v_mfma_f32_16x16x32_bf16 v[116:119], v[230:233], v[174:177], v[116:119]
	v_mfma_f32_16x16x32_bf16 v[108:111], v[238:241], v[174:177], v[108:111]
	v_mfma_f32_16x16x32_bf16 v[100:103], v[230:233], v[182:185], v[100:103]
	v_mfma_f32_16x16x32_bf16 v[92:95], v[238:241], v[182:185], v[92:95]
	v_mfma_f32_16x16x32_bf16 v[84:87], v[230:233], v[214:217], v[84:87]
	v_mfma_f32_16x16x32_bf16 v[76:79], v[238:241], v[214:217], v[76:79]
	v_mfma_f32_16x16x32_bf16 v[68:71], v[230:233], v[222:225], v[68:71]
	v_mfma_f32_16x16x32_bf16 v[64:67], v[238:241], v[222:225], v[64:67]
	s_setprio 0
	s_mov_b32 m0, s74
	v_lshl_add_u64 v[154:155], v[244:245], 0, s[62:63]
	s_barrier
	ds_read_b128 v[170:173], v157 offset:49152
	ds_read_b128 v[174:177], v157 offset:50176
	ds_read_b128 v[178:181], v157 offset:51200
	ds_read_b128 v[182:185], v157 offset:52224
	ds_read_b128 v[198:201], v157 offset:53248
	ds_read_b128 v[214:217], v157 offset:54272
	ds_read_b128 v[218:221], v157 offset:55296
	ds_read_b128 v[222:225], v157 offset:56320
	global_load_lds_dwordx4 v[154:155], off
	v_lshl_add_u64 v[154:155], v[246:247], 0, s[62:63]
	s_mov_b32 m0, s75
	s_nop 0
	global_load_lds_dwordx4 v[154:155], off
	s_barrier
	s_waitcnt lgkmcnt(0)
	s_setprio 1
	s_waitcnt lgkmcnt(0)
	v_mfma_f32_16x16x32_bf16 v[60:63], v[150:153], v[170:173], v[60:63]
	v_mfma_f32_16x16x32_bf16 v[56:59], v[162:165], v[170:173], v[56:59]
	v_mfma_f32_16x16x32_bf16 v[48:51], v[150:153], v[178:181], v[48:51]
	v_mfma_f32_16x16x32_bf16 v[40:43], v[162:165], v[178:181], v[40:43]
	v_mfma_f32_16x16x32_bf16 v[32:35], v[150:153], v[198:201], v[32:35]
	v_mfma_f32_16x16x32_bf16 v[24:27], v[162:165], v[198:201], v[24:27]
	v_mfma_f32_16x16x32_bf16 v[16:19], v[150:153], v[218:221], v[16:19]
	v_mfma_f32_16x16x32_bf16 v[8:11], v[162:165], v[218:221], v[8:11]
	v_mfma_f32_16x16x32_bf16 v[60:63], v[158:161], v[174:177], v[60:63]
	v_mfma_f32_16x16x32_bf16 v[56:59], v[166:169], v[174:177], v[56:59]
	v_mfma_f32_16x16x32_bf16 v[48:51], v[158:161], v[182:185], v[48:51]
	v_mfma_f32_16x16x32_bf16 v[40:43], v[166:169], v[182:185], v[40:43]
	v_mfma_f32_16x16x32_bf16 v[32:35], v[158:161], v[214:217], v[32:35]
	v_mfma_f32_16x16x32_bf16 v[24:27], v[166:169], v[214:217], v[24:27]
	v_mfma_f32_16x16x32_bf16 v[16:19], v[158:161], v[222:225], v[16:19]
	v_mfma_f32_16x16x32_bf16 v[8:11], v[166:169], v[222:225], v[8:11]
	s_setprio 0
	s_barrier
	s_mov_b32 m0, s94
	v_lshl_add_u64 v[150:151], s[26:27], 0, v[130:131]
	global_load_lds_dwordx4 v[150:151], off
	v_lshl_add_u64 v[150:151], s[26:27], 0, v[128:129]
	s_mov_b32 m0, s91
	s_nop 0
	global_load_lds_dwordx4 v[150:151], off
	s_waitcnt vmcnt(6)
	s_barrier
	s_setprio 1
	v_mfma_f32_16x16x32_bf16 v[52:55], v[226:229], v[170:173], v[52:55]
	v_mfma_f32_16x16x32_bf16 v[44:47], v[234:237], v[170:173], v[44:47]
	v_mfma_f32_16x16x32_bf16 v[36:39], v[226:229], v[178:181], v[36:39]
	v_mfma_f32_16x16x32_bf16 v[28:31], v[234:237], v[178:181], v[28:31]
	v_mfma_f32_16x16x32_bf16 v[20:23], v[226:229], v[198:201], v[20:23]
	v_mfma_f32_16x16x32_bf16 v[12:15], v[234:237], v[198:201], v[12:15]
	v_mfma_f32_16x16x32_bf16 v[4:7], v[226:229], v[218:221], v[4:7]
	v_mfma_f32_16x16x32_bf16 v[0:3], v[234:237], v[218:221], v[0:3]
	v_mfma_f32_16x16x32_bf16 v[52:55], v[230:233], v[174:177], v[52:55]
	v_mfma_f32_16x16x32_bf16 v[44:47], v[238:241], v[174:177], v[44:47]
	v_mfma_f32_16x16x32_bf16 v[36:39], v[230:233], v[182:185], v[36:39]
	v_mfma_f32_16x16x32_bf16 v[28:31], v[238:241], v[182:185], v[28:31]
	v_mfma_f32_16x16x32_bf16 v[20:23], v[230:233], v[214:217], v[20:23]
	v_mfma_f32_16x16x32_bf16 v[12:15], v[238:241], v[214:217], v[12:15]
	v_mfma_f32_16x16x32_bf16 v[4:7], v[230:233], v[222:225], v[4:7]
	v_mfma_f32_16x16x32_bf16 v[0:3], v[238:241], v[222:225], v[0:3]
	s_setprio 0
	s_movk_i32 s28, 0x100
	s_andn2_b64 vcc, exec, s[22:23]
	s_mov_b64 s[26:27], -1
	s_mov_b64 s[22:23], 0
	s_barrier
	s_cbranch_vccz .LBB0_2615
	v_lshl_or_b32 v162, s82, 8, v156
	v_ashrrev_i32_e32 v163, 31, v162
	v_lshlrev_b64 v[150:151], 2, v[162:163]
	v_lshl_add_u64 v[152:153], s[4:5], 0, v[150:151]
	global_load_dwordx4 v[214:217], v[152:153], off
	global_load_dwordx4 v[218:221], v[152:153], off offset:64
	global_load_dwordx4 v[222:225], v[152:153], off offset:512
	global_load_dwordx4 v[226:229], v[152:153], off offset:576
	s_ashr_i32 s9, s79, 31
	s_lshr_b32 s9, s9, 24
	s_add_i32 s9, s79, s9
	s_ashr_i32 s18, s9, 8
	s_ashr_i32 s19, s18, 31
	s_lshl_b64 s[18:19], s[18:19], 20
	s_add_u32 s18, s68, s18
	s_addc_u32 s19, s69, s19
	v_or_b32_e32 v154, 16, v162
	v_lshl_add_u64 v[164:165], s[18:19], 0, v[132:133]
	v_ashrrev_i32_e32 v155, 31, v154
	v_lshl_add_u64 v[164:165], v[164:165], 0, v[150:151]
	v_lshl_add_u64 v[154:155], v[154:155], 2, s[4:5]
	s_mov_b32 s82, s8
	s_mov_b64 s[20:21], s[14:15]
	s_mov_b32 s79, s10
	s_and_b64 vcc, exec, s[12:13]
	s_waitcnt vmcnt(0)
	v_pk_mul_f32 v[126:127], v[126:127], v[216:217]
	v_pk_mul_f32 v[124:125], v[124:125], v[214:215]
	global_store_dwordx4 v[164:165], v[124:127], off
	s_nop 1
	v_pk_mul_f32 v[122:123], v[122:123], v[220:221]
	v_or_b32_e32 v124, 0x80, v162
	v_ashrrev_i32_e32 v125, 31, v124
	v_pk_mul_f32 v[120:121], v[120:121], v[218:219]
	v_lshl_add_u64 v[124:125], v[124:125], 2, s[4:5]
	global_store_dwordx4 v[164:165], v[120:123], off offset:64
	s_nop 1
	v_pk_mul_f32 v[118:119], v[118:119], v[224:225]
	v_or_b32_e32 v120, 0x90, v162
	v_ashrrev_i32_e32 v121, 31, v120
	v_pk_mul_f32 v[116:117], v[116:117], v[222:223]
	v_lshl_add_u64 v[120:121], v[120:121], 2, s[4:5]
	global_store_dwordx4 v[164:165], v[116:119], off offset:512
	s_nop 1
	v_pk_mul_f32 v[110:111], v[110:111], v[228:229]
	v_pk_mul_f32 v[108:109], v[108:109], v[226:227]
	global_store_dwordx4 v[164:165], v[108:111], off offset:576
	s_nop 1
	v_lshl_add_u64 v[116:117], s[18:19], 0, v[134:135]
	v_lshl_add_u64 v[116:117], v[116:117], 0, v[150:151]
	v_pk_mul_f32 v[110:111], v[114:115], v[216:217]
	v_pk_mul_f32 v[108:109], v[112:113], v[214:215]
	global_store_dwordx4 v[116:117], v[108:111], off
	s_nop 1
	v_pk_mul_f32 v[106:107], v[106:107], v[220:221]
	v_pk_mul_f32 v[104:105], v[104:105], v[218:219]
	global_store_dwordx4 v[116:117], v[104:107], off offset:64
	s_nop 1
	v_pk_mul_f32 v[102:103], v[102:103], v[224:225]
	v_pk_mul_f32 v[100:101], v[100:101], v[222:223]
	global_store_dwordx4 v[116:117], v[100:103], off offset:512
	s_nop 1
	v_pk_mul_f32 v[94:95], v[94:95], v[228:229]
	v_pk_mul_f32 v[92:93], v[92:93], v[226:227]
	global_store_dwordx4 v[116:117], v[92:95], off offset:576
	s_nop 1
	v_lshl_add_u64 v[100:101], s[18:19], 0, v[136:137]
	v_lshl_add_u64 v[100:101], v[100:101], 0, v[150:151]
	v_pk_mul_f32 v[94:95], v[98:99], v[216:217]
	v_pk_mul_f32 v[92:93], v[96:97], v[214:215]
	global_store_dwordx4 v[100:101], v[92:95], off
	s_nop 1
	v_pk_mul_f32 v[90:91], v[90:91], v[220:221]
	v_pk_mul_f32 v[88:89], v[88:89], v[218:219]
	global_store_dwordx4 v[100:101], v[88:91], off offset:64
	s_nop 1
	v_pk_mul_f32 v[86:87], v[86:87], v[224:225]
	v_pk_mul_f32 v[84:85], v[84:85], v[222:223]
	global_store_dwordx4 v[100:101], v[84:87], off offset:512
	s_nop 1
	v_pk_mul_f32 v[78:79], v[78:79], v[228:229]
	v_pk_mul_f32 v[76:77], v[76:77], v[226:227]
	global_store_dwordx4 v[100:101], v[76:79], off offset:576
	s_nop 1
	v_lshl_add_u64 v[84:85], s[18:19], 0, v[138:139]
	v_lshl_add_u64 v[84:85], v[84:85], 0, v[150:151]
	v_pk_mul_f32 v[78:79], v[82:83], v[216:217]
	v_pk_mul_f32 v[76:77], v[80:81], v[214:215]
	global_store_dwordx4 v[84:85], v[76:79], off
	s_nop 1
	v_pk_mul_f32 v[74:75], v[74:75], v[220:221]
	v_pk_mul_f32 v[72:73], v[72:73], v[218:219]
	global_store_dwordx4 v[84:85], v[72:75], off offset:64
	s_nop 1
	v_pk_mul_f32 v[70:71], v[70:71], v[224:225]
	v_pk_mul_f32 v[68:69], v[68:69], v[222:223]
	global_store_dwordx4 v[84:85], v[68:71], off offset:512
	s_nop 1
	v_pk_mul_f32 v[66:67], v[66:67], v[228:229]
	v_pk_mul_f32 v[64:65], v[64:65], v[226:227]
	global_store_dwordx4 v[84:85], v[64:67], off offset:576
	s_nop 1
	v_lshl_add_u64 v[68:69], s[18:19], 0, v[140:141]
	v_lshl_add_u64 v[68:69], v[68:69], 0, v[150:151]
	v_pk_mul_f32 v[62:63], v[62:63], v[216:217]
	v_pk_mul_f32 v[60:61], v[60:61], v[214:215]
	global_store_dwordx4 v[68:69], v[60:63], off
	s_nop 1
	v_pk_mul_f32 v[58:59], v[58:59], v[220:221]
	v_pk_mul_f32 v[56:57], v[56:57], v[218:219]
	global_store_dwordx4 v[68:69], v[56:59], off offset:64
	s_nop 1
	v_pk_mul_f32 v[54:55], v[54:55], v[224:225]
	v_pk_mul_f32 v[52:53], v[52:53], v[222:223]
	global_store_dwordx4 v[68:69], v[52:55], off offset:512
	s_nop 1
	v_pk_mul_f32 v[46:47], v[46:47], v[228:229]
	v_pk_mul_f32 v[44:45], v[44:45], v[226:227]
	global_store_dwordx4 v[68:69], v[44:47], off offset:576
	s_nop 1
	v_lshl_add_u64 v[52:53], s[18:19], 0, v[142:143]
	v_lshl_add_u64 v[52:53], v[52:53], 0, v[150:151]
	v_pk_mul_f32 v[46:47], v[50:51], v[216:217]
	v_pk_mul_f32 v[44:45], v[48:49], v[214:215]
	global_store_dwordx4 v[52:53], v[44:47], off
	s_nop 1
	v_pk_mul_f32 v[42:43], v[42:43], v[220:221]
	v_pk_mul_f32 v[40:41], v[40:41], v[218:219]
	global_store_dwordx4 v[52:53], v[40:43], off offset:64
	s_nop 1
	v_pk_mul_f32 v[38:39], v[38:39], v[224:225]
	v_pk_mul_f32 v[36:37], v[36:37], v[222:223]
	global_store_dwordx4 v[52:53], v[36:39], off offset:512
	s_nop 1
	v_pk_mul_f32 v[30:31], v[30:31], v[228:229]
	v_pk_mul_f32 v[28:29], v[28:29], v[226:227]
	global_store_dwordx4 v[52:53], v[28:31], off offset:576
	s_nop 1
	v_lshl_add_u64 v[36:37], s[18:19], 0, v[146:147]
	v_lshl_add_u64 v[36:37], v[36:37], 0, v[150:151]
	v_pk_mul_f32 v[30:31], v[34:35], v[216:217]
	v_pk_mul_f32 v[28:29], v[32:33], v[214:215]
	global_store_dwordx4 v[36:37], v[28:31], off
	s_nop 1
	v_pk_mul_f32 v[26:27], v[26:27], v[220:221]
	v_pk_mul_f32 v[24:25], v[24:25], v[218:219]
	global_store_dwordx4 v[36:37], v[24:27], off offset:64
	s_nop 1
	v_pk_mul_f32 v[22:23], v[22:23], v[224:225]
	v_pk_mul_f32 v[20:21], v[20:21], v[222:223]
	global_store_dwordx4 v[36:37], v[20:23], off offset:512
	s_nop 1
	v_pk_mul_f32 v[14:15], v[14:15], v[228:229]
	v_pk_mul_f32 v[12:13], v[12:13], v[226:227]
	global_store_dwordx4 v[36:37], v[12:15], off offset:576
	s_nop 1
	v_lshl_add_u64 v[20:21], s[18:19], 0, v[148:149]
	v_lshl_add_u64 v[20:21], v[20:21], 0, v[150:151]
	s_mov_b64 s[18:19], s[16:17]
	v_pk_mul_f32 v[14:15], v[18:19], v[216:217]
	v_pk_mul_f32 v[12:13], v[16:17], v[214:215]
	global_store_dwordx4 v[20:21], v[12:15], off
	s_nop 1
	v_pk_mul_f32 v[10:11], v[10:11], v[220:221]
	v_pk_mul_f32 v[8:9], v[8:9], v[218:219]
	global_store_dwordx4 v[20:21], v[8:11], off offset:64
	s_nop 1
	v_pk_mul_f32 v[6:7], v[6:7], v[224:225]
	v_pk_mul_f32 v[4:5], v[4:5], v[222:223]
	global_store_dwordx4 v[20:21], v[4:7], off offset:512
	s_nop 1
	v_pk_mul_f32 v[2:3], v[2:3], v[228:229]
	v_pk_mul_f32 v[0:1], v[0:1], v[226:227]
	global_store_dwordx4 v[20:21], v[0:3], off offset:576
	s_nop 1
	s_cbranch_vccz .LBB0_2612
; #define PG8_WAIT_V(n) asm volatile("s_waitcnt vmcnt(" #n ")" ::: "memory")
; #define PG8_BAR __builtin_amdgcn_s_barrier()
; template <class Epi, class Sched>
; __device__ __forceinline__ void gemm_phase(LAS unsigned char* lds, const Gemm g, const Sched& S, const Epi& E) {
;     ...
;   PG8_WAIT_V(0);
;   if (wr == 0) PG8_BAR;
;   PG8_BAR;
	s_waitcnt vmcnt(0)
	v_readlane_b32 s82, v255, 17
	v_readlane_b32 s68, v255, 20
	s_cmpk_gt_u32 s24, 0xff
	v_readlane_b32 s83, v255, 18
	s_mov_b32 s74, 0x8000
	s_mov_b32 s75, 0x10000
	s_movk_i32 s79, 0x40ff
	s_movk_i32 s78, 0x2000
	v_readlane_b32 s69, v255, 21
	s_cbranch_scc1 .LBB0_2619
	s_barrier

; __device__ __forceinline__ void norm_phase(float* __restrict__ X, bf16_t* __restrict__ H, const float* __restrict__ nw, const float* __restrict__ modL, const float* __restrict__ modC, int sh_off, int sc_off, ...
;     ...
;     if (r < NCTX && nsl > 0) {
;       for (int sl = 0; sl < nsl; ++sl) { const float* pr = part + ((size_t)sl * NCTX + r) * DM;
; #pragma unroll
;         for (int i = 0; i < 4; ++i) v[i] += *(const f32x4*)(pr + i * 256 + lane * 4); }
; #pragma unroll
;       for (int i = 0; i < 4; ++i) *(f32x4*)(xr + i * 256 + lane * 4) = v[i];
;     }
.LBB0_2709:
	s_or_b64 exec, exec, s[20:21]
	s_and_b64 s[8:9], exec, s[8:9]
	v_readlane_b32 s20, v255, 22
	s_or_b64 s[16:17], s[8:9], s[16:17]
	v_cmp_lt_i32_e64 s[8:9], s81, v56
	v_readlane_b32 s21, v255, 23
	s_nor_b64 s[22:23], s[20:21], s[8:9]
	s_and_saveexec_b64 s[20:21], s[22:23]
	s_cbranch_execz .LBB0_2700
	v_lshl_add_u64 v[60:61], v[42:43], 0, v[40:41]
	v_add_co_u32_e32 v62, vcc, 0x9bce000, v60
	s_nop 1
	v_addc_co_u32_e32 v63, vcc, 0, v61, vcc
	global_load_dwordx4 v[74:77], v[62:63], off offset:256
	global_load_dwordx4 v[78:81], v[62:63], off offset:1280
	global_load_dwordx4 v[82:85], v[62:63], off offset:2304
	global_load_dwordx4 v[86:89], v[62:63], off offset:3328
	v_add_co_u32_e32 v62, vcc, 0x9cce000, v60
	s_nop 1
	v_addc_co_u32_e32 v63, vcc, 0, v61, vcc
	global_load_dwordx4 v[90:93], v[62:63], off offset:256
	global_load_dwordx4 v[94:97], v[62:63], off offset:1280
	global_load_dwordx4 v[98:101], v[62:63], off offset:2304
	global_load_dwordx4 v[102:105], v[62:63], off offset:3328
	v_add_co_u32_e32 v62, vcc, 0x9dce000, v60
	s_nop 1
	v_addc_co_u32_e32 v63, vcc, 0, v61, vcc
	global_load_dwordx4 v[106:109], v[62:63], off offset:256
	global_load_dwordx4 v[110:113], v[62:63], off offset:1280
	global_load_dwordx4 v[114:117], v[62:63], off offset:2304
	global_load_dwordx4 v[118:121], v[62:63], off offset:3328
	v_add_co_u32_e32 v62, vcc, 0x9ece000, v60
	s_nop 1
	v_addc_co_u32_e32 v63, vcc, 0, v61, vcc
	global_load_dwordx4 v[122:125], v[62:63], off offset:256
	global_load_dwordx4 v[126:129], v[62:63], off offset:1280
	global_load_dwordx4 v[130:133], v[62:63], off offset:2304
	global_load_dwordx4 v[134:137], v[62:63], off offset:3328
	s_waitcnt vmcnt(15)
	v_pk_add_f32 v[34:35], v[34:35], v[76:77]
	v_pk_add_f32 v[32:33], v[32:33], v[74:75]
	s_waitcnt vmcnt(14)
	v_pk_add_f32 v[30:31], v[30:31], v[80:81]
	v_pk_add_f32 v[28:29], v[28:29], v[78:79]
	s_waitcnt vmcnt(13)
	v_pk_add_f32 v[26:27], v[26:27], v[84:85]
	v_pk_add_f32 v[24:25], v[24:25], v[82:83]
	s_waitcnt vmcnt(12)
	v_pk_add_f32 v[10:11], v[10:11], v[88:89]
	v_pk_add_f32 v[8:9], v[8:9], v[86:87]
	s_waitcnt vmcnt(11)
	v_pk_add_f32 v[34:35], v[34:35], v[92:93]
	v_pk_add_f32 v[32:33], v[32:33], v[90:91]
	s_waitcnt vmcnt(10)
	v_pk_add_f32 v[30:31], v[30:31], v[96:97]
	v_pk_add_f32 v[28:29], v[28:29], v[94:95]
	s_waitcnt vmcnt(9)
	v_pk_add_f32 v[26:27], v[26:27], v[100:101]
	v_pk_add_f32 v[24:25], v[24:25], v[98:99]
	s_waitcnt vmcnt(8)
	v_pk_add_f32 v[10:11], v[10:11], v[104:105]
	v_pk_add_f32 v[8:9], v[8:9], v[102:103]
	s_waitcnt vmcnt(7)
	v_pk_add_f32 v[34:35], v[34:35], v[108:109]
	v_pk_add_f32 v[32:33], v[32:33], v[106:107]
	s_waitcnt vmcnt(6)
	v_pk_add_f32 v[30:31], v[30:31], v[112:113]
	v_pk_add_f32 v[28:29], v[28:29], v[110:111]
	s_waitcnt vmcnt(5)
	v_pk_add_f32 v[26:27], v[26:27], v[116:117]
	v_pk_add_f32 v[24:25], v[24:25], v[114:115]
	s_waitcnt vmcnt(4)
	v_pk_add_f32 v[10:11], v[10:11], v[120:121]
	v_pk_add_f32 v[8:9], v[8:9], v[118:119]
	s_waitcnt vmcnt(3)
	v_pk_add_f32 v[34:35], v[34:35], v[124:125]
	v_pk_add_f32 v[32:33], v[32:33], v[122:123]
	s_waitcnt vmcnt(2)
	v_pk_add_f32 v[30:31], v[30:31], v[128:129]
	v_pk_add_f32 v[28:29], v[28:29], v[126:127]
	s_waitcnt vmcnt(1)
	v_pk_add_f32 v[26:27], v[26:27], v[132:133]
	v_pk_add_f32 v[24:25], v[24:25], v[130:131]
	s_waitcnt vmcnt(0)
	v_pk_add_f32 v[10:11], v[10:11], v[136:137]
	v_pk_add_f32 v[8:9], v[8:9], v[134:135]
	v_lshl_add_u64 v[56:57], v[46:47], 0, v[40:41]
	global_store_dwordx4 v[56:57], v[32:35], off
	global_store_dwordx4 v[56:57], v[28:31], off offset:1024
	global_store_dwordx4 v[56:57], v[24:27], off offset:2048
	global_store_dwordx4 v[56:57], v[8:11], off offset:3072
	s_branch .LBB0_2700

; #define PG8_STAGE(bufoff, gbase, voff) do { _Pragma("unroll") for (int _i = 0; _i < 2; ++_i) \
;     __builtin_amdgcn_global_load_lds((const unsigned*)((const char*)(gbase) + (voff)[_i]), (LAS unsigned*)(lds + (bufoff) + ldsw + _i * 8192), 16, 0, 0); } while (0)
; #define PG8_LDA(dst, b, h) do { _Pragma("unroll") for (int m = 0; m < 4; ++m) _Pragma("unroll") for (int k = 0; k < 2; ++k) dst[m][k] = *(const LAS bf16x8*)(lds + PG8_SA(b, h) + aoff + m * 2048 + k * 1024); } while (0)
; #define PG8_LDB(dst, b, h) do { _Pragma("unroll") for (int n = 0; n < 2; ++n) _Pragma("unroll") for (int k = 0; k < 2; ++k) dst[n][k] = *(const LAS bf16x8*)(lds + PG8_SB(b, h) + boff + n * 2048 + k * 1024); } while (0)
; #define PG8_MMA(ai, bj, At, Bt) do { __builtin_amdgcn_s_setprio(1); _Pragma("unroll") for (int m = 0; m < 4; ++m) _Pragma("unroll") for (int n = 0; n < 2; ++n) _Pragma("unroll") for (int k = 0; k < 2; ++k) \
;     acc[ai][bj][m][n] = __builtin_amdgcn_mfma_f32_16x16x32_bf16(Bt[n][k], At[m][k], acc[ai][bj][m][n], 0, 0, 0); __builtin_amdgcn_s_setprio(0); } while (0)
; #define PG8_WAIT_V(n) asm volatile("s_waitcnt vmcnt(" #n ")" ::: "memory")
; #define PG8_WAIT_L(n) asm volatile("s_waitcnt lgkmcnt(" #n ")" ::: "memory")
; #define PG8_BAR __builtin_amdgcn_s_barrier()
; #define PG8_SCHED __builtin_amdgcn_sched_barrier(0)
; template <class Epi, class Sched>
; __device__ __forceinline__ void gemm_phase(LAS unsigned char* lds, const Gemm g, const Sched& S, const Epi& E) {
;     ...
;     for (int t = 0; t < nt; t += 2) {
;       const bool last = (t == nt - 2);
;       const char* a1 = cA + (size_t)(t + 1) * kstep;
;       const char* a2 = last ? nA : cA + (size_t)(t + 2) * kstep; const char* b2 = last ? nB : cB + (size_t)(t + 2) * kstep;
;       const char* a3 = a2 + kstep; const char* b3 = b2 + kstep;
;       PG8_LDB(B0, 0, 0); PG8_SCHED; PG8_LDA(At, 0, 0); PG8_STAGE(PG8_SA(1, 1), a1 + hstepA, voffA);
;       PG8_WAIT_L(8); PG8_BAR; PG8_WAIT_L(0); PG8_MMA(0, 0, At, B0); PG8_BAR; PG8_SCHED;
;       PG8_LDB(B1, 0, 1); PG8_STAGE(PG8_SB(0, 0), b2, voffB);
;       PG8_BAR; PG8_WAIT_L(0); PG8_MMA(0, 1, At, B1); PG8_BAR;
;       PG8_LDA(At, 0, 1); PG8_STAGE(PG8_SA(0, 0), a2, voffA);
;       PG8_BAR; PG8_WAIT_L(0); PG8_MMA(1, 0, At, B0); PG8_BAR; PG8_SCHED;
;       PG8_STAGE(PG8_SB(0, 1), b2 + hstepB, voffB);
;       PG8_WAIT_V(6); PG8_BAR; PG8_MMA(1, 1, At, B1); PG8_BAR;
.LBB0_2839:
	s_add_u32 s26, s22, 0xfff00080
	s_addc_u32 s27, s23, -1
	s_add_i32 s74, 16, 0x10000
	v_add_u32_e32 v158, s74, v145
	ds_read_b128 v[154:157], v158
	ds_read_b128 v[162:165], v158 offset:1024
	ds_read_b128 v[166:169], v158 offset:2048
	ds_read_b128 v[170:173], v158 offset:3072
	s_cmp_eq_u32 s69, 4
	s_cselect_b32 s29, s15, s27
	s_cselect_b32 s28, s59, s26
	s_cselect_b32 s27, s11, s68
	s_cselect_b32 s26, s66, s67
	v_lshl_add_u64 v[158:159], s[22:23], 0, v[150:151]
	s_add_i32 m0, s37, 0xc000
	ds_read_b128 v[174:177], v161
	ds_read_b128 v[178:181], v161 offset:1024
	ds_read_b128 v[182:185], v161 offset:2048
	ds_read_b128 v[198:201], v161 offset:3072
	ds_read_b128 v[214:217], v161 offset:4096
	ds_read_b128 v[218:221], v161 offset:5120
	ds_read_b128 v[222:225], v161 offset:6144
	ds_read_b128 v[226:229], v161 offset:7168
	global_load_lds_dwordx4 v[158:159], off
	v_lshl_add_u64 v[158:159], s[22:23], 0, v[152:153]
	s_add_i32 m0, s37, 0xe000
	s_nop 0
	global_load_lds_dwordx4 v[158:159], off
	s_waitcnt lgkmcnt(8)
	s_barrier
	s_waitcnt lgkmcnt(0)
	s_setprio 1
	s_waitcnt lgkmcnt(0)
	v_mfma_f32_16x16x32_bf16 v[124:127], v[154:157], v[174:177], v[124:127]
	v_mfma_f32_16x16x32_bf16 v[120:123], v[166:169], v[174:177], v[120:123]
	v_mfma_f32_16x16x32_bf16 v[112:115], v[154:157], v[182:185], v[112:115]
	v_mfma_f32_16x16x32_bf16 v[104:107], v[166:169], v[182:185], v[104:107]
	v_mfma_f32_16x16x32_bf16 v[96:99], v[154:157], v[214:217], v[96:99]
	v_mfma_f32_16x16x32_bf16 v[88:91], v[166:169], v[214:217], v[88:91]
	v_mfma_f32_16x16x32_bf16 v[80:83], v[154:157], v[222:225], v[80:83]
	v_mfma_f32_16x16x32_bf16 v[72:75], v[166:169], v[222:225], v[72:75]
	v_mfma_f32_16x16x32_bf16 v[124:127], v[162:165], v[178:181], v[124:127]
	v_mfma_f32_16x16x32_bf16 v[120:123], v[170:173], v[178:181], v[120:123]
	v_mfma_f32_16x16x32_bf16 v[112:115], v[162:165], v[198:201], v[112:115]
	v_mfma_f32_16x16x32_bf16 v[104:107], v[170:173], v[198:201], v[104:107]
	v_mfma_f32_16x16x32_bf16 v[96:99], v[162:165], v[218:221], v[96:99]
	v_mfma_f32_16x16x32_bf16 v[88:91], v[170:173], v[218:221], v[88:91]
	v_mfma_f32_16x16x32_bf16 v[80:83], v[162:165], v[226:229], v[80:83]
	v_mfma_f32_16x16x32_bf16 v[72:75], v[170:173], v[226:229], v[72:75]
	s_setprio 0
	s_barrier
	s_add_i32 s76, 16, 0x14000
	v_add_u32_e32 v158, s76, v145
	s_add_i32 s74, s74, s36
	ds_read_b128 v[230:233], v158
	ds_read_b128 v[234:237], v158 offset:1024
	ds_read_b128 v[238:241], v158 offset:2048
	ds_read_b128 v[242:245], v158 offset:3072
	v_lshl_add_u64 v[158:159], s[26:27], 0, v[130:131]
	s_mov_b32 m0, s74
	v_lshl_add_u64 v[246:247], s[26:27], 0, v[128:129]
	global_load_lds_dwordx4 v[158:159], off
	s_add_i32 m0, s74, 0x2000
	s_nop 0
	global_load_lds_dwordx4 v[246:247], off
	s_barrier
	s_waitcnt lgkmcnt(0)
	s_setprio 1
	s_waitcnt lgkmcnt(0)
	v_mfma_f32_16x16x32_bf16 v[116:119], v[230:233], v[174:177], v[116:119]
	v_mfma_f32_16x16x32_bf16 v[108:111], v[238:241], v[174:177], v[108:111]
	v_mfma_f32_16x16x32_bf16 v[100:103], v[230:233], v[182:185], v[100:103]
	v_mfma_f32_16x16x32_bf16 v[92:95], v[238:241], v[182:185], v[92:95]
	v_mfma_f32_16x16x32_bf16 v[84:87], v[230:233], v[214:217], v[84:87]
	v_mfma_f32_16x16x32_bf16 v[76:79], v[238:241], v[214:217], v[76:79]
	v_mfma_f32_16x16x32_bf16 v[68:71], v[230:233], v[222:225], v[68:71]
	v_mfma_f32_16x16x32_bf16 v[64:67], v[238:241], v[222:225], v[64:67]
	v_mfma_f32_16x16x32_bf16 v[116:119], v[234:237], v[178:181], v[116:119]
	v_mfma_f32_16x16x32_bf16 v[108:111], v[242:245], v[178:181], v[108:111]
	v_mfma_f32_16x16x32_bf16 v[100:103], v[234:237], v[198:201], v[100:103]
	v_mfma_f32_16x16x32_bf16 v[92:95], v[242:245], v[198:201], v[92:95]
	v_mfma_f32_16x16x32_bf16 v[84:87], v[234:237], v[218:221], v[84:87]
	v_mfma_f32_16x16x32_bf16 v[76:79], v[242:245], v[218:221], v[76:79]
	v_mfma_f32_16x16x32_bf16 v[68:71], v[234:237], v[226:229], v[68:71]
	v_mfma_f32_16x16x32_bf16 v[64:67], v[242:245], v[226:229], v[64:67]
	s_setprio 0
	s_mov_b32 m0, s37
	v_lshl_add_u64 v[248:249], s[28:29], 0, v[130:131]
	s_barrier
	ds_read_b128 v[174:177], v161 offset:16384
	ds_read_b128 v[178:181], v161 offset:17408
	ds_read_b128 v[182:185], v161 offset:18432
	ds_read_b128 v[198:201], v161 offset:19456
	ds_read_b128 v[214:217], v161 offset:20480
	ds_read_b128 v[218:221], v161 offset:21504
	ds_read_b128 v[222:225], v161 offset:22528
	ds_read_b128 v[226:229], v161 offset:23552
	global_load_lds_dwordx4 v[248:249], off
	v_lshl_add_u64 v[250:251], s[28:29], 0, v[128:129]
	s_mov_b32 m0, s38
	s_nop 0
	global_load_lds_dwordx4 v[250:251], off
	s_barrier
	s_waitcnt lgkmcnt(0)
	s_setprio 1
	s_waitcnt lgkmcnt(0)
	v_mfma_f32_16x16x32_bf16 v[60:63], v[154:157], v[174:177], v[60:63]
	v_mfma_f32_16x16x32_bf16 v[56:59], v[166:169], v[174:177], v[56:59]
	v_mfma_f32_16x16x32_bf16 v[48:51], v[154:157], v[182:185], v[48:51]
	v_mfma_f32_16x16x32_bf16 v[40:43], v[166:169], v[182:185], v[40:43]
	v_mfma_f32_16x16x32_bf16 v[32:35], v[154:157], v[214:217], v[32:35]
	v_mfma_f32_16x16x32_bf16 v[24:27], v[166:169], v[214:217], v[24:27]
	v_mfma_f32_16x16x32_bf16 v[16:19], v[154:157], v[222:225], v[16:19]
	v_mfma_f32_16x16x32_bf16 v[8:11], v[166:169], v[222:225], v[8:11]
	v_mfma_f32_16x16x32_bf16 v[60:63], v[162:165], v[178:181], v[60:63]
	v_mfma_f32_16x16x32_bf16 v[56:59], v[170:173], v[178:181], v[56:59]
	v_mfma_f32_16x16x32_bf16 v[48:51], v[162:165], v[198:201], v[48:51]
	v_mfma_f32_16x16x32_bf16 v[40:43], v[170:173], v[198:201], v[40:43]
	v_mfma_f32_16x16x32_bf16 v[32:35], v[162:165], v[218:221], v[32:35]
	v_mfma_f32_16x16x32_bf16 v[24:27], v[170:173], v[218:221], v[24:27]
	v_mfma_f32_16x16x32_bf16 v[16:19], v[162:165], v[226:229], v[16:19]
	v_mfma_f32_16x16x32_bf16 v[8:11], v[170:173], v[226:229], v[8:11]
	s_setprio 0
	s_barrier
; #define PG8_STAGE(bufoff, gbase, voff) do { _Pragma("unroll") for (int _i = 0; _i < 2; ++_i) \
;     __builtin_amdgcn_global_load_lds((const unsigned*)((const char*)(gbase) + (voff)[_i]), (LAS unsigned*)(lds + (bufoff) + ldsw + _i * 8192), 16, 0, 0); } while (0)
; #define PG8_LDA(dst, b, h) do { _Pragma("unroll") for (int m = 0; m < 4; ++m) _Pragma("unroll") for (int k = 0; k < 2; ++k) dst[m][k] = *(const LAS bf16x8*)(lds + PG8_SA(b, h) + aoff + m * 2048 + k * 1024); } while (0)
; #define PG8_LDB(dst, b, h) do { _Pragma("unroll") for (int n = 0; n < 2; ++n) _Pragma("unroll") for (int k = 0; k < 2; ++k) dst[n][k] = *(const LAS bf16x8*)(lds + PG8_SB(b, h) + boff + n * 2048 + k * 1024); } while (0)
; #define PG8_MMA(ai, bj, At, Bt) do { __builtin_amdgcn_s_setprio(1); _Pragma("unroll") for (int m = 0; m < 4; ++m) _Pragma("unroll") for (int n = 0; n < 2; ++n) _Pragma("unroll") for (int k = 0; k < 2; ++k) \
;     acc[ai][bj][m][n] = __builtin_amdgcn_mfma_f32_16x16x32_bf16(Bt[n][k], At[m][k], acc[ai][bj][m][n], 0, 0, 0); __builtin_amdgcn_s_setprio(0); } while (0)
; #define PG8_WAIT_V(n) asm volatile("s_waitcnt vmcnt(" #n ")" ::: "memory")
; #define PG8_WAIT_L(n) asm volatile("s_waitcnt lgkmcnt(" #n ")" ::: "memory")
; #define PG8_BAR __builtin_amdgcn_s_barrier()
; #define PG8_SCHED __builtin_amdgcn_sched_barrier(0)
; template <class Epi, class Sched>
; __device__ __forceinline__ void gemm_phase(LAS unsigned char* lds, const Gemm g, const Sched& S, const Epi& E) {
;     ...
;       PG8_BAR; PG8_WAIT_L(0); PG8_MMA(1, 0, At, B0); PG8_BAR; PG8_SCHED;
;       PG8_STAGE(PG8_SB(0, 1), b2 + hstepB, voffB);
;       PG8_WAIT_V(6); PG8_BAR; PG8_MMA(1, 1, At, B1); PG8_BAR;
;       PG8_LDB(B0, 1, 0); PG8_SCHED; PG8_LDA(At, 1, 0); PG8_STAGE(PG8_SA(0, 1), a2 + hstepA, voffA);
;       PG8_WAIT_L(8); PG8_BAR; PG8_WAIT_L(0); PG8_MMA(0, 0, At, B0); PG8_BAR; PG8_SCHED;
;       PG8_LDB(B1, 1, 1); PG8_STAGE(PG8_SB(1, 0), b3, voffB);
;       PG8_BAR; PG8_WAIT_L(0); PG8_MMA(0, 1, At, B1); PG8_BAR;
;       PG8_LDA(At, 1, 1); PG8_STAGE(PG8_SA(1, 0), a3, voffA);
;       PG8_BAR; PG8_WAIT_L(0); PG8_MMA(1, 0, At, B0); PG8_BAR; PG8_SCHED;
	s_add_u32 s74, s26, 0x100000
	s_addc_u32 s75, s27, 0
	s_add_i32 s76, s76, s36
	v_lshl_add_u64 v[154:155], s[74:75], 0, v[130:131]
	s_mov_b32 m0, s76
	s_nop 0
	global_load_lds_dwordx4 v[154:155], off
	v_lshl_add_u64 v[154:155], s[74:75], 0, v[128:129]
	s_add_i32 m0, s76, 0x2000
	s_nop 0
	global_load_lds_dwordx4 v[154:155], off
	s_waitcnt vmcnt(6)
	s_barrier
	s_setprio 1
	v_mfma_f32_16x16x32_bf16 v[52:55], v[230:233], v[174:177], v[52:55]
	v_mfma_f32_16x16x32_bf16 v[44:47], v[238:241], v[174:177], v[44:47]
	v_mfma_f32_16x16x32_bf16 v[36:39], v[230:233], v[182:185], v[36:39]
	v_mfma_f32_16x16x32_bf16 v[28:31], v[238:241], v[182:185], v[28:31]
	v_mfma_f32_16x16x32_bf16 v[20:23], v[230:233], v[214:217], v[20:23]
	v_mfma_f32_16x16x32_bf16 v[12:15], v[238:241], v[214:217], v[12:15]
	v_mfma_f32_16x16x32_bf16 v[4:7], v[230:233], v[222:225], v[4:7]
	v_mfma_f32_16x16x32_bf16 v[0:3], v[238:241], v[222:225], v[0:3]
	v_mfma_f32_16x16x32_bf16 v[52:55], v[234:237], v[178:181], v[52:55]
	v_mfma_f32_16x16x32_bf16 v[44:47], v[242:245], v[178:181], v[44:47]
	v_mfma_f32_16x16x32_bf16 v[36:39], v[234:237], v[198:201], v[36:39]
	v_mfma_f32_16x16x32_bf16 v[28:31], v[242:245], v[198:201], v[28:31]
	v_mfma_f32_16x16x32_bf16 v[20:23], v[234:237], v[218:221], v[20:23]
	v_mfma_f32_16x16x32_bf16 v[12:15], v[242:245], v[218:221], v[12:15]
	v_mfma_f32_16x16x32_bf16 v[4:7], v[234:237], v[226:229], v[4:7]
	v_mfma_f32_16x16x32_bf16 v[0:3], v[242:245], v[226:229], v[0:3]
	s_setprio 0
	s_add_i32 s74, 16, 0x18000
	v_add_u32_e32 v170, s74, v145
	s_barrier
	ds_read_b128 v[154:157], v170
	ds_read_b128 v[162:165], v170 offset:1024
	ds_read_b128 v[166:169], v170 offset:2048
	ds_read_b128 v[170:173], v170 offset:3072
	s_add_u32 s28, s28, 0x100000
	s_addc_u32 s29, s29, 0
	s_mov_b32 m0, s39
	v_lshl_add_u64 v[230:231], s[28:29], 0, v[130:131]
	ds_read_b128 v[174:177], v161 offset:32768
	ds_read_b128 v[178:181], v161 offset:33792
	ds_read_b128 v[182:185], v161 offset:34816
	ds_read_b128 v[198:201], v161 offset:35840
	ds_read_b128 v[214:217], v161 offset:36864
	ds_read_b128 v[218:221], v161 offset:37888
	ds_read_b128 v[222:225], v161 offset:38912
	ds_read_b128 v[226:229], v161 offset:39936
	global_load_lds_dwordx4 v[230:231], off
	v_lshl_add_u64 v[230:231], s[28:29], 0, v[128:129]
	s_mov_b32 m0, s44
	s_nop 0
	global_load_lds_dwordx4 v[230:231], off
	s_waitcnt lgkmcnt(8)
	s_barrier
	s_waitcnt lgkmcnt(0)
	s_setprio 1
	s_waitcnt lgkmcnt(0)
	v_mfma_f32_16x16x32_bf16 v[124:127], v[154:157], v[174:177], v[124:127]
	v_mfma_f32_16x16x32_bf16 v[120:123], v[166:169], v[174:177], v[120:123]
	v_mfma_f32_16x16x32_bf16 v[112:115], v[154:157], v[182:185], v[112:115]
	v_mfma_f32_16x16x32_bf16 v[104:107], v[166:169], v[182:185], v[104:107]
	v_mfma_f32_16x16x32_bf16 v[96:99], v[154:157], v[214:217], v[96:99]
	v_mfma_f32_16x16x32_bf16 v[88:91], v[166:169], v[214:217], v[88:91]
	v_mfma_f32_16x16x32_bf16 v[80:83], v[154:157], v[222:225], v[80:83]
	v_mfma_f32_16x16x32_bf16 v[72:75], v[166:169], v[222:225], v[72:75]
	v_mfma_f32_16x16x32_bf16 v[124:127], v[162:165], v[178:181], v[124:127]
	v_mfma_f32_16x16x32_bf16 v[120:123], v[170:173], v[178:181], v[120:123]
	v_mfma_f32_16x16x32_bf16 v[112:115], v[162:165], v[198:201], v[112:115]
	v_mfma_f32_16x16x32_bf16 v[104:107], v[170:173], v[198:201], v[104:107]
	v_mfma_f32_16x16x32_bf16 v[96:99], v[162:165], v[218:221], v[96:99]
	v_mfma_f32_16x16x32_bf16 v[88:91], v[170:173], v[218:221], v[88:91]
	v_mfma_f32_16x16x32_bf16 v[80:83], v[162:165], v[226:229], v[80:83]
	v_mfma_f32_16x16x32_bf16 v[72:75], v[170:173], v[226:229], v[72:75]
	s_setprio 0
	s_barrier
	s_add_i32 s28, 16, 0x1c000
	s_add_i32 s29, s74, s36
	v_add_u32_e32 v189, s28, v145
	v_lshl_add_u64 v[158:159], v[158:159], 0, s[62:63]
	s_mov_b32 m0, s29
	ds_read_b128 v[230:233], v189
	ds_read_b128 v[234:237], v189 offset:1024
	ds_read_b128 v[238:241], v189 offset:2048
	ds_read_b128 v[242:245], v189 offset:3072
	global_load_lds_dwordx4 v[158:159], off
	v_lshl_add_u64 v[158:159], v[246:247], 0, s[62:63]
	s_add_i32 m0, s29, 0x2000
	s_nop 0
	global_load_lds_dwordx4 v[158:159], off
	s_barrier
	s_waitcnt lgkmcnt(0)
	s_setprio 1
	s_waitcnt lgkmcnt(0)
	v_mfma_f32_16x16x32_bf16 v[116:119], v[230:233], v[174:177], v[116:119]
	v_mfma_f32_16x16x32_bf16 v[108:111], v[238:241], v[174:177], v[108:111]
	v_mfma_f32_16x16x32_bf16 v[100:103], v[230:233], v[182:185], v[100:103]
	v_mfma_f32_16x16x32_bf16 v[92:95], v[238:241], v[182:185], v[92:95]
	v_mfma_f32_16x16x32_bf16 v[84:87], v[230:233], v[214:217], v[84:87]
	v_mfma_f32_16x16x32_bf16 v[76:79], v[238:241], v[214:217], v[76:79]
	v_mfma_f32_16x16x32_bf16 v[68:71], v[230:233], v[222:225], v[68:71]
	v_mfma_f32_16x16x32_bf16 v[64:67], v[238:241], v[222:225], v[64:67]
	v_mfma_f32_16x16x32_bf16 v[116:119], v[234:237], v[178:181], v[116:119]
	v_mfma_f32_16x16x32_bf16 v[108:111], v[242:245], v[178:181], v[108:111]
	v_mfma_f32_16x16x32_bf16 v[100:103], v[234:237], v[198:201], v[100:103]
	v_mfma_f32_16x16x32_bf16 v[92:95], v[242:245], v[198:201], v[92:95]
	v_mfma_f32_16x16x32_bf16 v[84:87], v[234:237], v[218:221], v[84:87]
	v_mfma_f32_16x16x32_bf16 v[76:79], v[242:245], v[218:221], v[76:79]
	v_mfma_f32_16x16x32_bf16 v[68:71], v[234:237], v[226:229], v[68:71]
	v_mfma_f32_16x16x32_bf16 v[64:67], v[242:245], v[226:229], v[64:67]
	s_setprio 0
	s_mov_b32 m0, s47
	v_lshl_add_u64 v[158:159], v[248:249], 0, s[62:63]
	s_barrier
	ds_read_b128 v[174:177], v161 offset:49152
	ds_read_b128 v[178:181], v161 offset:50176
	ds_read_b128 v[182:185], v161 offset:51200
	ds_read_b128 v[198:201], v161 offset:52224
	ds_read_b128 v[214:217], v161 offset:53248
	ds_read_b128 v[218:221], v161 offset:54272
	ds_read_b128 v[222:225], v161 offset:55296
	ds_read_b128 v[226:229], v161 offset:56320
	global_load_lds_dwordx4 v[158:159], off
	v_lshl_add_u64 v[158:159], v[250:251], 0, s[62:63]
	s_mov_b32 m0, s48
	s_nop 0
	global_load_lds_dwordx4 v[158:159], off
	s_barrier
; #define PG8_STAGE(bufoff, gbase, voff) do { _Pragma("unroll") for (int _i = 0; _i < 2; ++_i) \
;     __builtin_amdgcn_global_load_lds((const unsigned*)((const char*)(gbase) + (voff)[_i]), (LAS unsigned*)(lds + (bufoff) + ldsw + _i * 8192), 16, 0, 0); } while (0)
; #define PG8_MMA(ai, bj, At, Bt) do { __builtin_amdgcn_s_setprio(1); _Pragma("unroll") for (int m = 0; m < 4; ++m) _Pragma("unroll") for (int n = 0; n < 2; ++n) _Pragma("unroll") for (int k = 0; k < 2; ++k) \
;     acc[ai][bj][m][n] = __builtin_amdgcn_mfma_f32_16x16x32_bf16(Bt[n][k], At[m][k], acc[ai][bj][m][n], 0, 0, 0); __builtin_amdgcn_s_setprio(0); } while (0)
; #define PG8_WAIT_V(n) asm volatile("s_waitcnt vmcnt(" #n ")" ::: "memory")
; #define PG8_WAIT_L(n) asm volatile("s_waitcnt lgkmcnt(" #n ")" ::: "memory")
; #define PG8_BAR __builtin_amdgcn_s_barrier()
; #define PG8_SCHED __builtin_amdgcn_sched_barrier(0)
; template <class Epi, class Sched>
; __device__ __forceinline__ void gemm_phase(LAS unsigned char* lds, const Gemm g, const Sched& S, const Epi& E) {
;     ...
;       PG8_BAR; PG8_WAIT_L(0); PG8_MMA(1, 0, At, B0); PG8_BAR; PG8_SCHED;
;       PG8_STAGE(PG8_SB(1, 1), b3 + hstepB, voffB);
;       PG8_WAIT_V(6); PG8_BAR; PG8_MMA(1, 1, At, B1); PG8_BAR;
;     }
;     E(acc, cur, wr, wc, fr, fq);
	s_waitcnt lgkmcnt(0)
	s_setprio 1
	s_waitcnt lgkmcnt(0)
	v_mfma_f32_16x16x32_bf16 v[60:63], v[154:157], v[174:177], v[60:63]
	v_mfma_f32_16x16x32_bf16 v[56:59], v[166:169], v[174:177], v[56:59]
	v_mfma_f32_16x16x32_bf16 v[48:51], v[154:157], v[182:185], v[48:51]
	v_mfma_f32_16x16x32_bf16 v[40:43], v[166:169], v[182:185], v[40:43]
	v_mfma_f32_16x16x32_bf16 v[32:35], v[154:157], v[214:217], v[32:35]
	v_mfma_f32_16x16x32_bf16 v[24:27], v[166:169], v[214:217], v[24:27]
	v_mfma_f32_16x16x32_bf16 v[16:19], v[154:157], v[222:225], v[16:19]
	v_mfma_f32_16x16x32_bf16 v[8:11], v[166:169], v[222:225], v[8:11]
	v_mfma_f32_16x16x32_bf16 v[60:63], v[162:165], v[178:181], v[60:63]
	v_mfma_f32_16x16x32_bf16 v[56:59], v[170:173], v[178:181], v[56:59]
	v_mfma_f32_16x16x32_bf16 v[48:51], v[162:165], v[198:201], v[48:51]
	v_mfma_f32_16x16x32_bf16 v[40:43], v[170:173], v[198:201], v[40:43]
	v_mfma_f32_16x16x32_bf16 v[32:35], v[162:165], v[218:221], v[32:35]
	v_mfma_f32_16x16x32_bf16 v[24:27], v[170:173], v[218:221], v[24:27]
	v_mfma_f32_16x16x32_bf16 v[16:19], v[162:165], v[226:229], v[16:19]
	v_mfma_f32_16x16x32_bf16 v[8:11], v[170:173], v[226:229], v[8:11]
	s_setprio 0
	s_barrier
	s_add_u32 s26, s26, 0x100080
	s_addc_u32 s27, s27, 0
	s_add_i32 s28, s28, s36
	v_lshl_add_u64 v[154:155], s[26:27], 0, v[130:131]
	s_mov_b32 m0, s28
	s_nop 0
	global_load_lds_dwordx4 v[154:155], off
	v_lshl_add_u64 v[154:155], s[26:27], 0, v[128:129]
	s_add_i32 m0, s28, 0x2000
	s_nop 0
	global_load_lds_dwordx4 v[154:155], off
	s_waitcnt vmcnt(6)
	s_barrier
	s_setprio 1
	v_mfma_f32_16x16x32_bf16 v[52:55], v[230:233], v[174:177], v[52:55]
	v_mfma_f32_16x16x32_bf16 v[44:47], v[238:241], v[174:177], v[44:47]
	v_mfma_f32_16x16x32_bf16 v[36:39], v[230:233], v[182:185], v[36:39]
	v_mfma_f32_16x16x32_bf16 v[28:31], v[238:241], v[182:185], v[28:31]
	v_mfma_f32_16x16x32_bf16 v[20:23], v[230:233], v[214:217], v[20:23]
	v_mfma_f32_16x16x32_bf16 v[12:15], v[238:241], v[214:217], v[12:15]
	v_mfma_f32_16x16x32_bf16 v[4:7], v[230:233], v[222:225], v[4:7]
	v_mfma_f32_16x16x32_bf16 v[0:3], v[238:241], v[222:225], v[0:3]
	v_mfma_f32_16x16x32_bf16 v[52:55], v[234:237], v[178:181], v[52:55]
	v_mfma_f32_16x16x32_bf16 v[44:47], v[242:245], v[178:181], v[44:47]
	v_mfma_f32_16x16x32_bf16 v[36:39], v[234:237], v[198:201], v[36:39]
	v_mfma_f32_16x16x32_bf16 v[28:31], v[242:245], v[198:201], v[28:31]
	v_mfma_f32_16x16x32_bf16 v[20:23], v[234:237], v[218:221], v[20:23]
	v_mfma_f32_16x16x32_bf16 v[12:15], v[242:245], v[218:221], v[12:15]
	v_mfma_f32_16x16x32_bf16 v[4:7], v[234:237], v[226:229], v[4:7]
	v_mfma_f32_16x16x32_bf16 v[0:3], v[242:245], v[226:229], v[0:3]
	s_setprio 0
	s_add_i32 s69, s69, 2
	s_add_u32 s22, s22, 0x100
	s_addc_u32 s23, s23, 0
	s_add_u32 s67, s67, 0x100
	s_addc_u32 s68, s68, 0
	s_cmp_gt_u32 s69, 5
	s_barrier
	s_cbranch_scc0 .LBB0_2839
	v_lshl_or_b32 v166, s58, 8, v160
	v_ashrrev_i32_e32 v167, 31, v166
	v_lshlrev_b64 v[154:155], 2, v[166:167]
	v_lshl_add_u64 v[156:157], s[8:9], 0, v[154:155]
	global_load_dwordx4 v[214:217], v[156:157], off
	global_load_dwordx4 v[218:221], v[156:157], off offset:64
	global_load_dwordx4 v[222:225], v[156:157], off offset:512
	global_load_dwordx4 v[226:229], v[156:157], off offset:576
	s_ashr_i32 s11, s51, 31
	s_lshr_b32 s11, s11, 23
	s_add_i32 s11, s51, s11
	s_ashr_i32 s22, s11, 9
	s_ashr_i32 s23, s22, 31
	s_lshl_b64 s[22:23], s[22:23], 20
	s_add_u32 s22, s45, s22
	s_addc_u32 s23, s46, s23
	v_or_b32_e32 v158, 16, v166
	v_lshl_add_u64 v[168:169], s[22:23], 0, v[132:133]
	v_ashrrev_i32_e32 v159, 31, v158
	v_lshl_add_u64 v[168:169], v[168:169], 0, v[154:155]
	v_lshl_add_u64 v[158:159], v[158:159], 2, s[8:9]
	s_mov_b32 s58, s10
	s_mov_b64 s[26:27], s[20:21]
	s_mov_b32 s51, s14
	s_and_b64 vcc, exec, s[16:17]
	s_waitcnt vmcnt(0)
	v_pk_mul_f32 v[126:127], v[126:127], v[216:217]
	v_pk_mul_f32 v[124:125], v[124:125], v[214:215]
	global_store_dwordx4 v[168:169], v[124:127], off
	s_nop 1
	v_pk_mul_f32 v[122:123], v[122:123], v[220:221]
	v_or_b32_e32 v124, 0x80, v166
	v_ashrrev_i32_e32 v125, 31, v124
	v_pk_mul_f32 v[120:121], v[120:121], v[218:219]
	v_lshl_add_u64 v[124:125], v[124:125], 2, s[8:9]
	global_store_dwordx4 v[168:169], v[120:123], off offset:64
	s_nop 1
	v_pk_mul_f32 v[118:119], v[118:119], v[224:225]
	v_or_b32_e32 v120, 0x90, v166
	v_ashrrev_i32_e32 v121, 31, v120
	v_pk_mul_f32 v[116:117], v[116:117], v[222:223]
	v_lshl_add_u64 v[120:121], v[120:121], 2, s[8:9]
	global_store_dwordx4 v[168:169], v[116:119], off offset:512
	s_nop 1
	v_pk_mul_f32 v[110:111], v[110:111], v[228:229]
	v_pk_mul_f32 v[108:109], v[108:109], v[226:227]
	global_store_dwordx4 v[168:169], v[108:111], off offset:576
	s_nop 1
	v_lshl_add_u64 v[116:117], s[22:23], 0, v[134:135]
	v_lshl_add_u64 v[116:117], v[116:117], 0, v[154:155]
	v_pk_mul_f32 v[110:111], v[114:115], v[216:217]
	v_pk_mul_f32 v[108:109], v[112:113], v[214:215]
	global_store_dwordx4 v[116:117], v[108:111], off
	s_nop 1
	v_pk_mul_f32 v[106:107], v[106:107], v[220:221]
	v_pk_mul_f32 v[104:105], v[104:105], v[218:219]
	global_store_dwordx4 v[116:117], v[104:107], off offset:64
	s_nop 1
	v_pk_mul_f32 v[102:103], v[102:103], v[224:225]
	v_pk_mul_f32 v[100:101], v[100:101], v[222:223]
	global_store_dwordx4 v[116:117], v[100:103], off offset:512
	s_nop 1
	v_pk_mul_f32 v[94:95], v[94:95], v[228:229]
	v_pk_mul_f32 v[92:93], v[92:93], v[226:227]
	global_store_dwordx4 v[116:117], v[92:95], off offset:576
	s_nop 1
	v_lshl_add_u64 v[100:101], s[22:23], 0, v[136:137]
	v_lshl_add_u64 v[100:101], v[100:101], 0, v[154:155]
	v_pk_mul_f32 v[94:95], v[98:99], v[216:217]
	v_pk_mul_f32 v[92:93], v[96:97], v[214:215]
	global_store_dwordx4 v[100:101], v[92:95], off
	s_nop 1
	v_pk_mul_f32 v[90:91], v[90:91], v[220:221]
	v_pk_mul_f32 v[88:89], v[88:89], v[218:219]
	global_store_dwordx4 v[100:101], v[88:91], off offset:64
	s_nop 1
	v_pk_mul_f32 v[86:87], v[86:87], v[224:225]
	v_pk_mul_f32 v[84:85], v[84:85], v[222:223]
	global_store_dwordx4 v[100:101], v[84:87], off offset:512
	s_nop 1
	v_pk_mul_f32 v[78:79], v[78:79], v[228:229]
	v_pk_mul_f32 v[76:77], v[76:77], v[226:227]
	global_store_dwordx4 v[100:101], v[76:79], off offset:576
	s_nop 1
	v_lshl_add_u64 v[84:85], s[22:23], 0, v[138:139]
	v_lshl_add_u64 v[84:85], v[84:85], 0, v[154:155]
	v_pk_mul_f32 v[78:79], v[82:83], v[216:217]
	v_pk_mul_f32 v[76:77], v[80:81], v[214:215]
	global_store_dwordx4 v[84:85], v[76:79], off
	s_nop 1
	v_pk_mul_f32 v[74:75], v[74:75], v[220:221]
	v_pk_mul_f32 v[72:73], v[72:73], v[218:219]
	global_store_dwordx4 v[84:85], v[72:75], off offset:64
	s_nop 1
	v_pk_mul_f32 v[70:71], v[70:71], v[224:225]
	v_pk_mul_f32 v[68:69], v[68:69], v[222:223]
	global_store_dwordx4 v[84:85], v[68:71], off offset:512
	s_nop 1
	v_pk_mul_f32 v[66:67], v[66:67], v[228:229]
	v_pk_mul_f32 v[64:65], v[64:65], v[226:227]
	global_store_dwordx4 v[84:85], v[64:67], off offset:576
	s_nop 1
	v_lshl_add_u64 v[68:69], s[22:23], 0, v[140:141]
	v_lshl_add_u64 v[68:69], v[68:69], 0, v[154:155]
	v_pk_mul_f32 v[62:63], v[62:63], v[216:217]
	v_pk_mul_f32 v[60:61], v[60:61], v[214:215]
	global_store_dwordx4 v[68:69], v[60:63], off
	s_nop 1
	v_pk_mul_f32 v[58:59], v[58:59], v[220:221]
	v_pk_mul_f32 v[56:57], v[56:57], v[218:219]
	global_store_dwordx4 v[68:69], v[56:59], off offset:64
	s_nop 1
	v_pk_mul_f32 v[54:55], v[54:55], v[224:225]
	v_pk_mul_f32 v[52:53], v[52:53], v[222:223]
	global_store_dwordx4 v[68:69], v[52:55], off offset:512
	s_nop 1
	v_pk_mul_f32 v[46:47], v[46:47], v[228:229]
	v_pk_mul_f32 v[44:45], v[44:45], v[226:227]
	global_store_dwordx4 v[68:69], v[44:47], off offset:576
	s_nop 1
	v_lshl_add_u64 v[52:53], s[22:23], 0, v[142:143]
	v_lshl_add_u64 v[52:53], v[52:53], 0, v[154:155]
	v_pk_mul_f32 v[46:47], v[50:51], v[216:217]
	v_pk_mul_f32 v[44:45], v[48:49], v[214:215]
	global_store_dwordx4 v[52:53], v[44:47], off
	s_nop 1
	v_pk_mul_f32 v[42:43], v[42:43], v[220:221]
	v_pk_mul_f32 v[40:41], v[40:41], v[218:219]
	global_store_dwordx4 v[52:53], v[40:43], off offset:64
	s_nop 1
	v_pk_mul_f32 v[38:39], v[38:39], v[224:225]
	v_pk_mul_f32 v[36:37], v[36:37], v[222:223]
	global_store_dwordx4 v[52:53], v[36:39], off offset:512
	s_nop 1
	v_pk_mul_f32 v[30:31], v[30:31], v[228:229]
	v_pk_mul_f32 v[28:29], v[28:29], v[226:227]
	global_store_dwordx4 v[52:53], v[28:31], off offset:576
	s_nop 1
	v_lshl_add_u64 v[36:37], s[22:23], 0, v[146:147]
	v_lshl_add_u64 v[36:37], v[36:37], 0, v[154:155]
	v_pk_mul_f32 v[30:31], v[34:35], v[216:217]
	v_pk_mul_f32 v[28:29], v[32:33], v[214:215]
	global_store_dwordx4 v[36:37], v[28:31], off
	s_nop 1
	v_pk_mul_f32 v[26:27], v[26:27], v[220:221]
	v_pk_mul_f32 v[24:25], v[24:25], v[218:219]
	global_store_dwordx4 v[36:37], v[24:27], off offset:64
	s_nop 1
	v_pk_mul_f32 v[22:23], v[22:23], v[224:225]
	v_pk_mul_f32 v[20:21], v[20:21], v[222:223]
	global_store_dwordx4 v[36:37], v[20:23], off offset:512
	s_nop 1
	v_pk_mul_f32 v[14:15], v[14:15], v[228:229]
	v_pk_mul_f32 v[12:13], v[12:13], v[226:227]
	global_store_dwordx4 v[36:37], v[12:15], off offset:576
	s_nop 1
	v_lshl_add_u64 v[20:21], s[22:23], 0, v[148:149]
	v_lshl_add_u64 v[20:21], v[20:21], 0, v[154:155]
	s_mov_b64 s[22:23], s[18:19]
	v_pk_mul_f32 v[14:15], v[18:19], v[216:217]
	v_pk_mul_f32 v[12:13], v[16:17], v[214:215]
	global_store_dwordx4 v[20:21], v[12:15], off
	s_nop 1
	v_pk_mul_f32 v[10:11], v[10:11], v[220:221]
	v_pk_mul_f32 v[8:9], v[8:9], v[218:219]
	global_store_dwordx4 v[20:21], v[8:11], off offset:64
	s_nop 1
	v_pk_mul_f32 v[6:7], v[6:7], v[224:225]
	v_pk_mul_f32 v[4:5], v[4:5], v[222:223]
	global_store_dwordx4 v[20:21], v[4:7], off offset:512
	s_nop 1
	v_pk_mul_f32 v[2:3], v[2:3], v[228:229]
	v_pk_mul_f32 v[0:1], v[0:1], v[226:227]
	global_store_dwordx4 v[20:21], v[0:3], off offset:576
	s_nop 1
	s_cbranch_vccz .LBB0_2836
	s_waitcnt vmcnt(0)
	s_cmpk_gt_u32 s24, 0xff
	s_movk_i32 s48, 0x400
	s_movk_i32 s58, 0x6000
	s_movk_i32 s49, 0xc00
	s_movk_i32 s51, 0x4000
	s_cbranch_scc1 .LBB0_2843
	s_barrier
